# NSA block selection: tiles with <=16 valid blocks per token skip the rank computation (selection = valid mask)
# speedup vs baseline: 1.0010x; 1.0010x over previous
; DEVI float bf2f(bf16_t b) { return __uint_as_float(((unsigned)b) << 16); }
; DEVI float sigmoidf(float x) { return 1.f / (1.f + __expf(-x)); }
; DEVI void nsa_item(const Ctx& cx, const unsigned* cflag, int b, int g, int qt, unsigned char* lds, int wv) {
;     ...
;   {
;     const bf16_t* gp = proj + (size_t)(tokrow * (unsigned)PS + (unsigned)(C_GATE + g * 9));
; #pragma unroll
;     for (int c = 0; c < 3; ++c) {
;       const float gt = sigmoidf(bf2f(gp[c * 3 + 0]));
; #pragma unroll
;       for (int d = 0; d < 4; ++d) { scr[c * 4 + d] = o[c][d] * gt; o[c][d] = (f32x4){0.f, 0.f, 0.f, 0.f}; }
;       mr[c] = -1e29f; lrn[c] = 0.f;
;     }
;   }
;   __syncthreads();
;   {
;     const int tl2 = tid >> 2, sub = tid & 3;
;     const int cur = (t0 + tl2) >> 6;
.LBB0_1413:
	s_movk_i32 s0, 0x900
	v_mul_lo_u32 v0, v123, s0
	s_mul_i32 s21, s21, 9
	v_or_b32_e32 v0, s21, v0
	v_readlane_b32 s4, v252, 40
	v_add_u32_e32 v0, 0x380, v0
	v_mov_b32_e32 v1, v33
	v_readlane_b32 s6, v252, 42
	v_readlane_b32 s7, v252, 43
	v_and_b32_e32 v2, 0x3fffffc0, v119
	v_readlane_b32 s0, v253, 1
	v_lshl_add_u64 v[110:111], v[0:1], 1, s[6:7]
	global_load_ushort v0, v[110:111], off
	v_readlane_b32 s5, v252, 41
	s_waitcnt vmcnt(0)
	v_lshlrev_b32_e32 v0, 16, v0
	v_mul_f32_e32 v0, 0xbfb8aa3b, v0
	v_exp_f32_e32 v3, v0
	v_add_u32_e32 v0, s0, v2
	v_or_b32_e32 v0, v0, v120
	v_mul_lo_u32 v0, v0, 12
	v_add_f32_e32 v2, 1.0, v3
	v_div_scale_f32 v3, s[0:1], v2, v2, 1.0
	v_rcp_f32_e32 v4, v3
	v_readlane_b32 s0, v254, 6
	v_readlane_b32 s1, v254, 7
	s_nop 1
	v_lshl_add_u64 v[108:109], v[0:1], 4, s[0:1]
	v_fma_f32 v1, -v3, v4, 1.0
	v_div_scale_f32 v0, vcc, 1.0, v2, 1.0
	v_fmac_f32_e32 v4, v1, v4
	v_mul_f32_e32 v1, v0, v4
	v_fma_f32 v5, -v3, v1, v0
	v_fmac_f32_e32 v1, v5, v4
	v_fma_f32 v0, -v3, v1, v0
	v_div_fmas_f32 v0, v0, v4, v1
	v_div_fixup_f32 v12, v0, v2, 1.0
	v_pk_mul_f32 v[2:3], v[68:69], v[12:13] op_sel_hi:[1,0]
	v_pk_mul_f32 v[0:1], v[66:67], v[12:13] op_sel_hi:[1,0]
	v_pk_mul_f32 v[6:7], v[72:73], v[12:13] op_sel_hi:[1,0]
	v_pk_mul_f32 v[4:5], v[70:71], v[12:13] op_sel_hi:[1,0]
	v_pk_mul_f32 v[10:11], v[64:65], v[12:13] op_sel_hi:[1,0]
	v_pk_mul_f32 v[8:9], v[62:63], v[12:13] op_sel_hi:[1,0]
	v_pk_mul_f32 v[14:15], v[60:61], v[12:13] op_sel_hi:[1,0]
	v_pk_mul_f32 v[12:13], v[58:59], v[12:13] op_sel_hi:[1,0]
	global_store_dwordx4 v[108:109], v[0:3], off
	global_store_dwordx4 v[108:109], v[4:7], off offset:16
	global_store_dwordx4 v[108:109], v[8:11], off offset:32
	global_store_dwordx4 v[108:109], v[12:15], off offset:48
	global_load_ushort v0, v[110:111], off offset:6
	v_and_b32_e32 v72, 3, v116
	s_waitcnt vmcnt(0)
	v_lshlrev_b32_e32 v0, 16, v0
	v_mul_f32_e32 v0, 0xbfb8aa3b, v0
	v_exp_f32_e32 v0, v0
	s_nop 0
	v_add_f32_e32 v0, 1.0, v0
	v_div_scale_f32 v1, s[0:1], v0, v0, 1.0
	v_rcp_f32_e32 v2, v1
	v_div_scale_f32 v3, vcc, 1.0, v0, 1.0
	s_movk_i32 s0, 0x84
	v_fma_f32 v4, -v1, v2, 1.0
	v_fmac_f32_e32 v2, v4, v2
	v_mul_f32_e32 v4, v3, v2
	v_fma_f32 v5, -v1, v4, v3
	v_fmac_f32_e32 v4, v5, v2
	v_fma_f32 v1, -v1, v4, v3
	v_div_fmas_f32 v1, v1, v2, v4
	v_div_fixup_f32 v12, v1, v0, 1.0
	v_pk_mul_f32 v[2:3], v[56:57], v[12:13] op_sel_hi:[1,0]
	v_pk_mul_f32 v[0:1], v[54:55], v[12:13] op_sel_hi:[1,0]
	v_pk_mul_f32 v[6:7], v[52:53], v[12:13] op_sel_hi:[1,0]
	v_pk_mul_f32 v[4:5], v[50:51], v[12:13] op_sel_hi:[1,0]
	v_pk_mul_f32 v[10:11], v[48:49], v[12:13] op_sel_hi:[1,0]
	v_pk_mul_f32 v[8:9], v[46:47], v[12:13] op_sel_hi:[1,0]
	v_pk_mul_f32 v[14:15], v[44:45], v[12:13] op_sel_hi:[1,0]
	v_pk_mul_f32 v[12:13], v[42:43], v[12:13] op_sel_hi:[1,0]
	global_store_dwordx4 v[108:109], v[0:3], off offset:64
	global_store_dwordx4 v[108:109], v[4:7], off offset:80
	global_store_dwordx4 v[108:109], v[8:11], off offset:96
	global_store_dwordx4 v[108:109], v[12:15], off offset:112
	global_load_ushort v0, v[110:111], off offset:12
	v_mul_lo_u32 v1, v114, s0
	v_add_u32_e32 v70, 0, v1
	v_add_u32_e32 v20, 0xb004, v70
	v_add_u32_e32 v16, 0xf200, v70
	v_add_u32_e32 v17, 0xb00c, v70
	v_add_u32_e32 v18, 0xf208, v70
	v_add_u32_e32 v19, 0xb014, v70
	v_add_u32_e32 v22, 0xb01c, v70
	v_add_u32_e32 v42, 0xb024, v70
	v_add_u32_e32 v43, 0xf220, v70
	v_add_u32_e32 v44, 0xb02c, v70
	v_add_u32_e32 v46, 0xf228, v70
	v_add_u32_e32 v45, 0xb034, v70
	v_add_u32_e32 v48, 0xf230, v70
	v_add_u32_e32 v64, 0xb03c, v70
	v_add_u32_e32 v65, 0xf238, v70
	v_add_u32_e32 v49, 0xb04c, v70
	v_add_u32_e32 v73, 0xf240, v70
	v_add_u32_e32 v21, 0xf210, v70
	v_add_u32_e32 v23, 0xf218, v70
	v_add_u32_e32 v66, 0xb054, v70
	v_add_u32_e32 v67, 0xb044, v70
	v_add_u32_e32 v68, 0xf250, v70
	v_add_u32_e32 v69, 0xf248, v70
	v_add_u32_e32 v74, 0xb060, v70
	v_add_u32_e32 v75, 0xf25c, v70
	v_add_u32_e32 v76, 0xb068, v70
	v_add_u32_e32 v77, 0xf264, v70
	v_add_u32_e32 v78, 0xb070, v70
	v_add_u32_e32 v79, 0xf26c, v70
	v_add_u32_e32 v80, 0xb078, v70
	v_add_u32_e32 v81, 0xf274, v70
	v_lshl_add_u32 v71, v72, 5, v70
	s_waitcnt vmcnt(0)
	v_lshlrev_b32_e32 v0, 16, v0
	v_mul_f32_e32 v0, 0xbfb8aa3b, v0
	v_exp_f32_e32 v0, v0
	s_nop 0
	v_add_f32_e32 v0, 1.0, v0
	v_div_scale_f32 v1, s[0:1], v0, v0, 1.0
	v_rcp_f32_e32 v2, v1
	v_div_scale_f32 v3, vcc, 1.0, v0, 1.0
	v_cmp_ne_u32_e64 s[0:1], 0, v72
	v_fma_f32 v4, -v1, v2, 1.0
	v_fmac_f32_e32 v2, v4, v2
	v_mul_f32_e32 v4, v3, v2
	v_fma_f32 v5, -v1, v4, v3
	v_fmac_f32_e32 v4, v5, v2
	v_fma_f32 v1, -v1, v4, v3
	v_div_fmas_f32 v1, v1, v2, v4
	v_div_fixup_f32 v12, v1, v0, 1.0
	v_pk_mul_f32 v[2:3], v[40:41], v[12:13] op_sel_hi:[1,0]
	v_pk_mul_f32 v[0:1], v[38:39], v[12:13] op_sel_hi:[1,0]
	v_pk_mul_f32 v[6:7], v[36:37], v[12:13] op_sel_hi:[1,0]
	v_pk_mul_f32 v[4:5], v[34:35], v[12:13] op_sel_hi:[1,0]
	v_pk_mul_f32 v[10:11], v[30:31], v[12:13] op_sel_hi:[1,0]
	v_pk_mul_f32 v[8:9], v[28:29], v[12:13] op_sel_hi:[1,0]
	v_pk_mul_f32 v[14:15], v[26:27], v[12:13] op_sel_hi:[1,0]
	v_pk_mul_f32 v[12:13], v[24:25], v[12:13] op_sel_hi:[1,0]
	global_store_dwordx4 v[108:109], v[0:3], off offset:128
	global_store_dwordx4 v[108:109], v[4:7], off offset:144
	global_store_dwordx4 v[108:109], v[8:11], off offset:160
	global_store_dwordx4 v[108:109], v[12:15], off offset:176
	s_waitcnt lgkmcnt(0)
	s_barrier
	s_cmp_gt_u32 s3, 7
	s_cbranch_scc1 .Ltopk_rank
	v_add_u32_e32 v21, s20, v114
	v_ashrrev_i32_e32 v68, 6, v21
	v_lshlrev_b32_e64 v0, v68, 2
	v_add_u32_e32 v0, -1, v0
	v_cmp_eq_u32_e32 vcc, 0, v72
	s_movk_i32 s58, 0x80
	s_branch .Ltopk_join
; DEVI void nsa_item(const Ctx& cx, const unsigned* cflag, int b, int g, int qt, unsigned char* lds, int wv) {
;     ...
;     float a[32];
; #pragma unroll
;     for (int j = 0; j < 32; ++j) {
;       float raw = impA[tl2 * 33 + j] + (j > 0 ? impB[tl2 * 33 + j - 1] : 0.f);
;       bool valid = j <= cur, forced = (j == 0) | (j == cur) | (j == cur - 1);
;       a[j] = valid ? (forced ? 1e9f : raw) : -1e30f;
;     }
.Ltopk_rank:
	ds_read2_b32 v[58:59], v17 offset1:1
	ds_read2_b32 v[60:61], v18 offset1:1
	ds_read2_b32 v[54:55], v19 offset1:1
	ds_read2_b32 v[62:63], v16 offset1:1
	ds_read2_b32 v[56:57], v21 offset1:1
	ds_read2_b32 v[16:17], v22 offset1:1
	ds_read2_b32 v[12:13], v23 offset1:1
	ds_read2_b32 v[50:51], v42 offset1:1
	ds_read2_b32 v[52:53], v43 offset1:1
	ds_read2_b32 v[42:43], v45 offset1:1
	ds_read2_b32 v[44:45], v44 offset1:1
	ds_read2_b32 v[46:47], v46 offset1:1
	ds_read2_b32 v[24:25], v49 offset1:1
	ds_read2_b32 v[38:39], v67 offset1:1
	ds_read2_b32 v[34:35], v68 offset1:1
	ds_read2_b32 v[26:27], v69 offset1:1
	ds_read2_b32 v[48:49], v48 offset1:1
	ds_read2_b32 v[36:37], v66 offset1:1
	ds_read2_b32 v[28:29], v64 offset1:1
	ds_read2_b32 v[30:31], v65 offset1:1
	ds_read2_b32 v[40:41], v73 offset1:1
	ds_read2_b32 v[8:9], v76 offset1:1
	ds_read2_b32 v[10:11], v74 offset1:1
	ds_read2_b32 v[14:15], v75 offset1:1
	ds_read2_b32 v[0:1], v81 offset1:1
	ds_read2_b32 v[18:19], v77 offset1:1
	ds_read2_b32 v[2:3], v80 offset1:1
	ds_read2_b32 v[4:5], v78 offset1:1
	ds_read2_b32 v[6:7], v79 offset1:1
	ds_read2_b32 v[64:65], v20 offset1:1
	ds_read_b32 v20, v70 offset:45148
	ds_read_b32 v22, v70 offset:62040
	ds_read_b32 v73, v71 offset:45056
	v_cmp_eq_u32_e32 vcc, 0, v72
	v_mov_b32_e32 v74, 0
	s_and_saveexec_b64 s[4:5], s[0:1]
	ds_read_b32 v74, v71 offset:61948
	s_or_b64 exec, exec, s[4:5]
	v_add_u32_e32 v21, s20, v114
	v_ashrrev_i32_e32 v68, 6, v21
	v_add_u32_e32 v69, -1, v68
	v_cmp_gt_i32_e64 s[0:1], 0, v68
	v_and_b32_e32 v75, 0xffffff80, v21
	s_waitcnt lgkmcnt(14)
	v_pk_add_f32 v[58:59], v[58:59], v[60:61]
	v_cndmask_b32_e64 v67, v239, v238, s[0:1]
	s_waitcnt lgkmcnt(3)
	v_pk_add_f32 v[60:61], v[64:65], v[62:63]
	v_cmp_lt_u32_e64 s[0:1], 1, v69
	v_add_u32_e32 v21, -3, v68
	v_add_f32_e32 v13, v17, v13
	v_cndmask_b32_e64 v23, v239, v60, s[0:1]
	v_cmp_ne_u32_e64 s[0:1], s58, v75
	v_add_u32_e32 v17, -9, v68
	v_pk_add_f32 v[44:45], v[44:45], v[46:47]
	v_cndmask_b32_e64 v62, v239, v61, s[0:1]
	v_cmp_lt_u32_e64 s[0:1], 1, v21
	v_pk_add_f32 v[42:43], v[42:43], v[48:49]
	v_pk_add_f32 v[24:25], v[24:25], v[26:27]
	v_cndmask_b32_e64 v21, v239, v58, s[0:1]
	s_movk_i32 s0, 0x100
	v_cmp_ne_u32_e64 s[0:1], s0, v75
	v_pk_add_f32 v[26:27], v[28:29], v[30:31]
	v_pk_add_f32 v[38:39], v[38:39], v[40:41]
	v_cndmask_b32_e64 v58, v239, v59, s[0:1]
	v_cmp_lt_i32_e64 s[0:1], 3, v68
	v_pk_add_f32 v[34:35], v[36:37], v[34:35]
	v_pk_add_f32 v[10:11], v[10:11], v[14:15]
	v_cndmask_b32_e64 v60, v238, v58, s[0:1]
	v_cmp_lt_i32_e64 s[0:1], 2, v68
	v_pk_add_f32 v[8:9], v[8:9], v[18:19]
	v_subrev_u32_e32 v15, 25, v68
	v_cndmask_b32_e64 v61, v238, v21, s[0:1]
	v_cmp_lt_i32_e64 s[0:1], 1, v68
	v_add_f32_e32 v21, v54, v56
	v_pk_add_f32 v[0:1], v[2:3], v[0:1]
	v_cndmask_b32_e64 v59, v238, v62, s[0:1]
	v_cmp_lt_i32_e64 s[0:1], 0, v68
	v_pk_add_f32 v[2:3], v[4:5], v[6:7]
	v_lshlrev_b32_e32 v66, 3, v72
	v_cndmask_b32_e64 v58, v238, v23, s[0:1]
	v_add_u32_e32 v23, -5, v68
	v_cmp_lt_u32_e64 s[0:1], 1, v23
	v_cmp_eq_u32_e64 s[4:5], v66, v69
	v_cmp_ne_u32_e64 s[6:7], 0, v72
	v_cndmask_b32_e64 v21, v239, v21, s[0:1]
	v_cmp_lt_i32_e64 s[0:1], 4, v68
	v_lshlrev_b32_e64 v79, v66, 8
	v_lshlrev_b32_e64 v80, v66, 16
	v_cndmask_b32_e64 v56, v238, v21, s[0:1]
	s_movk_i32 s0, 0x180
	v_add_f32_e32 v21, v55, v57
	v_cmp_ne_u32_e64 s[0:1], s0, v75
	s_nop 1
	v_cndmask_b32_e64 v21, v239, v21, s[0:1]
	v_cmp_lt_i32_e64 s[0:1], 5, v68
	s_nop 1
	v_cndmask_b32_e64 v54, v238, v21, s[0:1]
	s_movk_i32 s0, 0x200
	v_cmp_ne_u32_e64 s[0:1], s0, v75
	s_nop 1
	v_cndmask_b32_e64 v13, v239, v13, s[0:1]
	v_cmp_lt_i32_e64 s[0:1], 7, v68
	s_nop 1
	v_cndmask_b32_e64 v55, v238, v13, s[0:1]
	v_add_f32_e32 v13, v50, v52
	v_cmp_lt_u32_e64 s[0:1], 1, v17
	v_add_u32_e32 v17, -11, v68
	s_nop 0
	v_cndmask_b32_e64 v13, v239, v13, s[0:1]
	v_cmp_lt_i32_e64 s[0:1], 8, v68
	s_nop 1
	v_cndmask_b32_e64 v50, v238, v13, s[0:1]
	v_add_f32_e32 v13, v51, v53
	v_cmp_ne_u32_e64 s[0:1], s60, v75
	s_nop 1
	v_cndmask_b32_e64 v13, v239, v13, s[0:1]
	v_cmp_lt_i32_e64 s[0:1], 9, v68
	s_nop 1
	v_cndmask_b32_e64 v51, v238, v13, s[0:1]
	v_add_u32_e32 v13, -13, v68
	v_cmp_lt_u32_e64 s[0:1], 1, v17
	s_nop 1
	v_cndmask_b32_e64 v17, v239, v44, s[0:1]
	v_cmp_lt_u32_e64 s[0:1], 1, v13
	s_nop 1
	v_cndmask_b32_e64 v13, v239, v42, s[0:1]
	s_movk_i32 s0, 0x300
	v_cmp_ne_u32_e64 s[0:1], s0, v75
	s_nop 1
	v_cndmask_b32_e64 v21, v239, v45, s[0:1]
	s_movk_i32 s0, 0x380
	v_cmp_ne_u32_e64 s[0:1], s0, v75
	s_nop 1
	v_cndmask_b32_e64 v23, v239, v43, s[0:1]
	v_cmp_lt_i32_e64 s[0:1], 12, v68
	s_nop 1
	v_cndmask_b32_e64 v45, v238, v13, s[0:1]
	v_cmp_lt_i32_e64 s[0:1], 10, v68
	v_subrev_u32_e32 v13, 19, v68
	s_nop 0
	v_cndmask_b32_e64 v44, v238, v17, s[0:1]
	v_cmp_lt_i32_e64 s[0:1], 13, v68
	v_add_u32_e32 v17, -15, v68
	s_nop 0
	v_cndmask_b32_e64 v43, v238, v23, s[0:1]
	v_cmp_lt_i32_e64 s[0:1], 11, v68
	s_nop 1
	v_cndmask_b32_e64 v42, v238, v21, s[0:1]
	v_cmp_lt_u32_e64 s[0:1], 1, v17
	s_nop 1
	v_cndmask_b32_e64 v17, v239, v26, s[0:1]
	v_cmp_lt_u32_e64 s[0:1], 1, v13
	s_nop 1
	v_cndmask_b32_e64 v13, v239, v24, s[0:1]
	s_movk_i32 s0, 0x400
	v_cmp_ne_u32_e64 s[0:1], s0, v75
	v_subrev_u32_e32 v24, 21, v68
	s_nop 0
	v_cndmask_b32_e64 v21, v239, v27, s[0:1]
	v_cmp_ne_u32_e64 s[0:1], s26, v75
	s_nop 1
	v_cndmask_b32_e64 v23, v239, v25, s[0:1]
	v_subrev_u32_e32 v25, 17, v68
	v_cmp_lt_u32_e64 s[0:1], 1, v25
	s_nop 1
	v_cndmask_b32_e64 v25, v239, v38, s[0:1]
	v_cmp_lt_u32_e64 s[0:1], 1, v24
	s_nop 1
	v_cndmask_b32_e64 v24, v239, v34, s[0:1]
	s_movk_i32 s0, 0x480
	v_cmp_ne_u32_e64 s[0:1], s0, v75
	s_nop 1
	v_cndmask_b32_e64 v30, v239, v39, s[0:1]
	s_movk_i32 s0, 0x580
	v_cmp_ne_u32_e64 s[0:1], s0, v75
	s_nop 1
	v_cndmask_b32_e64 v31, v239, v35, s[0:1]
	v_cmp_lt_i32_e64 s[0:1], 18, v68
	s_nop 1
	v_cndmask_b32_e64 v28, v238, v13, s[0:1]
	v_cmp_lt_i32_e64 s[0:1], 14, v68
	s_nop 1
	v_cndmask_b32_e64 v29, v238, v17, s[0:1]
	v_cmp_lt_i32_e64 s[0:1], 19, v68
	s_nop 1
	v_cndmask_b32_e64 v26, v238, v23, s[0:1]
	v_cmp_lt_i32_e64 s[0:1], 15, v68
	v_mov_b32_e32 v23, v12
	v_subrev_u32_e32 v12, 23, v68
	v_cndmask_b32_e64 v27, v238, v21, s[0:1]
	v_cmp_lt_i32_e64 s[0:1], 20, v68
	v_mov_b32_e32 v21, v16
	v_add_u32_e32 v16, -7, v68
	v_cndmask_b32_e64 v24, v238, v24, s[0:1]
	v_cmp_lt_i32_e64 s[0:1], 16, v68
	s_waitcnt lgkmcnt(1)
; DEVI void nsa_item(const Ctx& cx, const unsigned* cflag, int b, int g, int qt, unsigned char* lds, int wv) {
;     ...
;     float a[32];
; #pragma unroll
;     for (int j = 0; j < 32; ++j) {
;       float raw = impA[tl2 * 33 + j] + (j > 0 ? impB[tl2 * 33 + j - 1] : 0.f);
;       bool valid = j <= cur, forced = (j == 0) | (j == cur) | (j == cur - 1);
;       a[j] = valid ? (forced ? 1e9f : raw) : -1e30f;
;     }
;     unsigned bits = 0u;
; #pragma unroll
;     for (int e = 0; e < 8; ++e) {
;       const int m = sub * 8 + e;
;       float raw = impA[tl2 * 33 + m] + (m > 0 ? impB[tl2 * 33 + m - 1] : 0.f);
;       bool valid = m <= cur, forced = (m == 0) | (m == cur) | (m == cur - 1);
;       const float am = valid ? (forced ? 1e9f : raw) : -1e30f;
;       int rank = 0;
; #pragma unroll
;       for (int j = 0; j < 32; ++j) rank += (a[j] > am || (a[j] == am && j < m)) ? 1 : 0;
;       if (rank < 16 && valid) bits |= 1u << m;
	v_pk_add_f32 v[20:21], v[20:21], v[22:23]
	v_cndmask_b32_e64 v25, v238, v25, s[0:1]
	v_cmp_lt_i32_e64 s[0:1], 21, v68
	s_nop 1
	v_cndmask_b32_e64 v13, v238, v31, s[0:1]
	v_cmp_lt_i32_e64 s[0:1], 17, v68
	s_nop 1
	v_cndmask_b32_e64 v17, v238, v30, s[0:1]
	v_cmp_lt_u32_e64 s[0:1], 1, v16
	s_nop 1
	v_cndmask_b32_e64 v16, v239, v21, s[0:1]
	v_cmp_lt_u32_e64 s[0:1], 1, v12
	s_nop 1
	v_cndmask_b32_e64 v12, v239, v20, s[0:1]
	v_cmp_lt_i32_e64 s[0:1], 22, v68
	s_nop 1
	v_cndmask_b32_e64 v12, v238, v12, s[0:1]
	v_cmp_lt_i32_e64 s[0:1], 6, v68
	s_nop 1
	v_cndmask_b32_e64 v16, v238, v16, s[0:1]
	s_movk_i32 s0, 0x600
	v_cmp_ne_u32_e64 s[0:1], s0, v75
	s_nop 1
	v_cndmask_b32_e64 v14, v239, v10, s[0:1]
	s_movk_i32 s0, 0x680
	v_cmp_ne_u32_e64 s[0:1], s0, v75
	v_subrev_u32_e32 v10, 27, v68
	s_nop 0
	v_cndmask_b32_e64 v8, v239, v8, s[0:1]
	v_cmp_lt_u32_e64 s[0:1], 1, v15
	s_nop 1
	v_cndmask_b32_e64 v15, v239, v11, s[0:1]
	v_cmp_lt_u32_e64 s[0:1], 1, v10
	s_nop 1
	v_cndmask_b32_e64 v9, v239, v9, s[0:1]
	v_cmp_lt_i32_e64 s[0:1], 25, v68
	s_nop 1
	v_cndmask_b32_e64 v10, v238, v8, s[0:1]
	v_cmp_lt_i32_e64 s[0:1], 23, v68
	s_nop 1
	v_cndmask_b32_e64 v11, v238, v14, s[0:1]
	v_cmp_lt_i32_e64 s[0:1], 26, v68
	v_subrev_u32_e32 v14, 29, v68
	s_nop 0
	v_cndmask_b32_e64 v8, v238, v9, s[0:1]
	v_cmp_lt_i32_e64 s[0:1], 24, v68
	s_nop 1
	v_cndmask_b32_e64 v9, v238, v15, s[0:1]
	s_movk_i32 s0, 0x700
	v_cmp_ne_u32_e64 s[0:1], s0, v75
	v_subrev_u32_e32 v15, 31, v68
	s_nop 0
	v_cndmask_b32_e64 v2, v239, v2, s[0:1]
	v_cmp_lt_u32_e64 s[0:1], 1, v14
	s_nop 1
	v_cndmask_b32_e64 v3, v239, v3, s[0:1]
	s_movk_i32 s0, 0x780
	v_cmp_ne_u32_e64 s[0:1], s0, v75
	s_nop 1
	v_cndmask_b32_e64 v0, v239, v0, s[0:1]
	v_cmp_lt_u32_e64 s[0:1], 1, v15
	s_nop 1
	v_cndmask_b32_e64 v1, v239, v1, s[0:1]
	v_cmp_lt_i32_e64 s[0:1], 30, v68
	s_nop 1
	v_cndmask_b32_e64 v7, v238, v1, s[0:1]
	v_cmp_lt_i32_e64 s[0:1], 29, v68
	s_nop 1
	v_cndmask_b32_e64 v4, v238, v0, s[0:1]
	v_cmp_lt_i32_e64 s[0:1], 28, v68
	s_waitcnt lgkmcnt(0)
	v_add_f32_e32 v0, v73, v74
	v_cndmask_b32_e64 v6, v238, v3, s[0:1]
	v_cmp_lt_i32_e64 s[0:1], 27, v68
	s_nop 1
	v_cndmask_b32_e64 v5, v238, v2, s[0:1]
	v_cmp_eq_u32_e64 s[0:1], v66, v68
	s_or_b64 s[0:1], s[0:1], s[4:5]
	s_or_b64 s[0:1], vcc, s[0:1]
	v_cndmask_b32_e64 v0, v0, v239, s[0:1]
	v_cmp_le_i32_e64 s[0:1], v66, v68
	s_nop 1
	v_cndmask_b32_e64 v0, v238, v0, s[0:1]
	v_cmp_eq_f32_e64 s[4:5], v67, v0
	v_cmp_eq_f32_e64 s[10:11], v58, v0
	s_and_b64 s[68:69], s[6:7], s[4:5]
	v_cmp_gt_f32_e64 s[4:5], v58, v0
	s_and_b64 s[10:11], s[6:7], s[10:11]
	s_or_b64 s[4:5], s[4:5], s[10:11]
	v_cmp_eq_f32_e64 s[10:11], v59, v0
	v_cndmask_b32_e64 v1, 0, 1, s[4:5]
	v_cmp_gt_f32_e64 s[4:5], v59, v0
	s_and_b64 s[10:11], s[6:7], s[10:11]
	s_or_b64 s[4:5], s[4:5], s[10:11]
	v_cndmask_b32_e64 v2, 0, 1, s[4:5]
	v_cmp_eq_f32_e64 s[4:5], v61, v0
	v_cmp_eq_f32_e64 s[10:11], v60, v0
	s_and_b64 s[70:71], s[6:7], s[4:5]
	v_cmp_gt_f32_e64 s[4:5], v60, v0
	s_and_b64 s[10:11], s[6:7], s[10:11]
	s_or_b64 s[4:5], s[4:5], s[10:11]
	v_cndmask_b32_e64 v3, 0, 1, s[4:5]
	v_cmp_eq_f32_e64 s[4:5], v56, v0
	v_cmp_eq_f32_e64 s[10:11], v54, v0
	s_and_b64 s[72:73], s[6:7], s[4:5]
	v_cmp_gt_f32_e64 s[4:5], v54, v0
	s_and_b64 s[10:11], s[6:7], s[10:11]
	s_or_b64 s[4:5], s[4:5], s[10:11]
	v_cndmask_b32_e64 v20, 0, 1, s[4:5]
	v_cmp_eq_f32_e64 s[4:5], v16, v0
	s_and_b64 s[74:75], s[6:7], s[4:5]
	v_cmp_eq_f32_e64 s[46:47], v27, v0
	v_cmp_eq_u32_e64 s[4:5], 3, v72
	v_cmp_gt_f32_e64 s[18:19], v27, v0
	s_and_b64 s[46:47], s[4:5], s[46:47]
	s_or_b64 s[18:19], s[18:19], s[46:47]
	v_cmp_eq_f32_e64 s[46:47], v25, v0
	v_cmp_eq_f32_e64 s[48:49], v17, v0
	s_and_b64 s[60:61], s[4:5], s[46:47]
	v_cmp_gt_f32_e64 s[46:47], v17, v0
	s_and_b64 s[48:49], s[4:5], s[48:49]
	s_or_b64 s[46:47], s[46:47], s[48:49]
	v_cmp_eq_f32_e64 s[48:49], v28, v0
	v_cmp_eq_f32_e64 s[50:51], v26, v0
	s_and_b64 s[62:63], s[4:5], s[48:49]
	v_cmp_gt_f32_e64 s[48:49], v26, v0
	s_and_b64 s[50:51], s[4:5], s[50:51]
	s_or_b64 s[48:49], s[48:49], s[50:51]
	v_cmp_eq_f32_e64 s[50:51], v24, v0
	v_cmp_eq_f32_e64 s[58:59], v13, v0
	s_and_b64 s[64:65], s[4:5], s[50:51]
	v_cmp_gt_f32_e64 s[50:51], v13, v0
	s_and_b64 s[58:59], s[4:5], s[58:59]
	s_or_b64 s[50:51], s[50:51], s[58:59]
	v_cmp_eq_f32_e64 s[58:59], v12, v0
	s_and_b64 s[66:67], s[4:5], s[58:59]
	v_cmp_gt_f32_e64 s[58:59], v11, v0
	v_cmp_gt_f32_e64 s[8:9], v67, v0
	v_cmp_gt_f32_e64 s[52:53], v61, v0
	v_cndmask_b32_e64 v21, 0, 1, s[58:59]
	v_cmp_gt_f32_e64 s[58:59], v10, v0
	v_cmp_gt_f32_e64 s[54:55], v56, v0
	v_cmp_gt_f32_e64 s[56:57], v16, v0
	v_cndmask_b32_e64 v22, 0, 1, s[58:59]
	v_cmp_gt_f32_e64 s[58:59], v5, v0
	v_cmp_gt_f32_e64 s[34:35], v55, v0
	v_cmp_eq_f32_e64 s[44:45], v55, v0
	v_cndmask_b32_e64 v23, 0, 1, s[58:59]
	v_cmp_gt_f32_e64 s[58:59], v4, v0
	v_cmp_gt_f32_e64 s[10:11], v50, v0
	v_cmp_eq_f32_e64 s[40:41], v50, v0
	v_cndmask_b32_e64 v30, 0, 1, s[58:59]
	v_cmp_gt_f32_e64 s[58:59], v9, v0
	v_cmp_gt_f32_e64 s[26:27], v51, v0
	v_cmp_eq_f32_e64 s[42:43], v51, v0
	v_addc_co_u32_e64 v21, s[58:59], 0, v21, s[58:59]
	v_cmp_gt_f32_e64 s[58:59], v8, v0
	v_cmp_gt_f32_e64 s[12:13], v44, v0
	v_cmp_eq_f32_e64 s[36:37], v44, v0
	v_addc_co_u32_e64 v21, s[58:59], v21, v22, s[58:59]
	v_cmp_gt_f32_e64 s[58:59], v6, v0
	v_cmp_gt_f32_e64 s[22:23], v42, v0
	v_cmp_eq_f32_e64 s[38:39], v42, v0
	v_addc_co_u32_e64 v21, s[58:59], v21, v23, s[58:59]
	v_cmp_gt_f32_e64 s[58:59], v7, v0
	v_cmp_gt_f32_e64 s[14:15], v45, v0
	v_cmp_eq_f32_e64 s[28:29], v45, v0
	v_cmp_gt_f32_e64 s[20:21], v43, v0
	v_cmp_eq_f32_e64 s[30:31], v43, v0
	v_cmp_gt_f32_e64 s[16:17], v29, v0
	v_cmp_eq_f32_e64 s[24:25], v29, v0
	v_cndmask_b32_e64 v15, 0, 1, s[18:19]
; DEVI void nsa_item(const Ctx& cx, const unsigned* cflag, int b, int g, int qt, unsigned char* lds, int wv) {
;     ...
;     for (int e = 0; e < 8; ++e) {
;       const int m = sub * 8 + e;
;       float raw = impA[tl2 * 33 + m] + (m > 0 ? impB[tl2 * 33 + m - 1] : 0.f);
;       bool valid = m <= cur, forced = (m == 0) | (m == cur) | (m == cur - 1);
;       const float am = valid ? (forced ? 1e9f : raw) : -1e30f;
;       int rank = 0;
; #pragma unroll
;       for (int j = 0; j < 32; ++j) rank += (a[j] > am || (a[j] == am && j < m)) ? 1 : 0;
;       if (rank < 16 && valid) bits |= 1u << m;
	v_cmp_gt_f32_e64 s[18:19], v25, v0
	v_cndmask_b32_e64 v18, 0, 1, s[46:47]
	v_cmp_gt_f32_e64 s[46:47], v28, v0
	v_cndmask_b32_e64 v19, 0, 1, s[48:49]
	v_cmp_gt_f32_e64 s[48:49], v24, v0
	v_cndmask_b32_e64 v14, 0, 1, s[50:51]
	v_cmp_gt_f32_e64 s[50:51], v12, v0
	v_addc_co_u32_e64 v0, s[58:59], v21, v30, s[58:59]
	s_or_b64 s[8:9], s[8:9], s[68:69]
	v_addc_co_u32_e64 v0, s[8:9], v0, v1, s[8:9]
	s_or_b64 s[8:9], s[52:53], s[70:71]
	s_nop 0
	v_addc_co_u32_e64 v0, s[8:9], v0, v2, s[8:9]
	s_or_b64 s[8:9], s[54:55], s[72:73]
	s_nop 0
	v_addc_co_u32_e64 v0, s[8:9], v0, v3, s[8:9]
	s_or_b64 s[8:9], s[56:57], s[74:75]
	s_nop 0
	v_addc_co_u32_e64 v20, s[8:9], v0, v20, s[8:9]
	v_cmp_lt_u32_e64 s[8:9], 1, v72
	s_and_b64 s[44:45], s[44:45], s[8:9]
	s_or_b64 s[34:35], s[34:35], s[44:45]
	v_cndmask_b32_e64 v21, 0, 1, s[34:35]
	s_and_b64 s[34:35], s[40:41], s[8:9]
	s_and_b64 s[40:41], s[42:43], s[8:9]
	s_or_b64 s[26:27], s[26:27], s[40:41]
	s_or_b64 s[10:11], s[10:11], s[34:35]
	v_cndmask_b32_e64 v22, 0, 1, s[26:27]
	s_and_b64 s[26:27], s[36:37], s[8:9]
	s_and_b64 s[36:37], s[38:39], s[8:9]
	v_addc_co_u32_e64 v20, s[10:11], v20, v21, s[10:11]
	s_or_b64 s[22:23], s[22:23], s[36:37]
	s_or_b64 s[10:11], s[12:13], s[26:27]
	v_cndmask_b32_e64 v23, 0, 1, s[22:23]
	s_and_b64 s[22:23], s[28:29], s[8:9]
	s_and_b64 s[28:29], s[30:31], s[8:9]
	v_addc_co_u32_e64 v20, s[10:11], v20, v22, s[10:11]
	s_or_b64 s[20:21], s[20:21], s[28:29]
	s_or_b64 s[10:11], s[14:15], s[22:23]
	v_cndmask_b32_e64 v30, 0, 1, s[20:21]
	s_and_b64 s[20:21], s[24:25], s[8:9]
	v_addc_co_u32_e64 v20, s[10:11], v20, v23, s[10:11]
	s_or_b64 s[10:11], s[16:17], s[20:21]
	s_nop 0
	v_addc_co_u32_e64 v20, s[10:11], v20, v30, s[10:11]
	s_or_b64 s[10:11], s[18:19], s[60:61]
	v_add_u32_e32 v0, 0xb004, v71
	v_add_u32_e32 v2, 0xf200, v71
	v_addc_co_u32_e64 v15, s[10:11], v20, v15, s[10:11]
	ds_read2_b32 v[0:1], v0 offset1:1
	ds_read2_b32 v[2:3], v2 offset1:1
	s_or_b64 s[10:11], s[46:47], s[62:63]
	v_addc_co_u32_e64 v15, s[10:11], v15, v18, s[10:11]
	s_or_b64 s[10:11], s[48:49], s[64:65]
	s_nop 0
	v_addc_co_u32_e64 v15, s[10:11], v15, v19, s[10:11]
	v_or_b32_e32 v18, 1, v66
	v_cmp_eq_u32_e64 s[10:11], v18, v68
	v_cmp_eq_u32_e64 s[14:15], v18, v69
	s_waitcnt lgkmcnt(0)
	v_add_f32_e32 v0, v0, v2
	s_or_b64 s[10:11], s[10:11], s[14:15]
	v_cndmask_b32_e64 v0, v0, v239, s[10:11]
	v_cmp_lt_i32_e64 s[10:11], v66, v68
	s_or_b64 s[12:13], s[50:51], s[66:67]
	v_add_f32_e32 v1, v1, v3
	v_cndmask_b32_e64 v0, v238, v0, s[10:11]
	v_cmp_eq_f32_e64 s[58:59], v25, v0
	v_cmp_gt_f32_e64 s[56:57], v25, v0
	s_and_b64 s[58:59], s[4:5], s[58:59]
	s_or_b64 s[56:57], s[56:57], s[58:59]
	v_cmp_eq_f32_e64 s[58:59], v17, v0
	v_cmp_eq_f32_e64 s[60:61], v28, v0
	s_and_b64 s[74:75], s[4:5], s[58:59]
	v_cmp_gt_f32_e64 s[58:59], v28, v0
	s_and_b64 s[60:61], s[4:5], s[60:61]
	s_or_b64 s[58:59], s[58:59], s[60:61]
	v_cmp_eq_f32_e64 s[60:61], v26, v0
	v_cmp_eq_f32_e64 s[62:63], v24, v0
	s_and_b64 s[76:77], s[4:5], s[60:61]
	v_cmp_gt_f32_e64 s[60:61], v24, v0
	s_and_b64 s[62:63], s[4:5], s[62:63]
	v_cmp_ge_f32_e64 s[14:15], v67, v0
	v_cmp_eq_f32_e64 s[16:17], v58, v0
	s_or_b64 s[60:61], s[60:61], s[62:63]
	v_cmp_eq_f32_e64 s[62:63], v13, v0
	v_cmp_eq_f32_e64 s[64:65], v12, v0
	v_cndmask_b32_e64 v2, 0, 1, s[14:15]
	v_cmp_gt_f32_e64 s[14:15], v58, v0
	s_and_b64 s[16:17], s[6:7], s[16:17]
	s_and_b64 s[78:79], s[4:5], s[62:63]
	v_cmp_gt_f32_e64 s[62:63], v12, v0
	s_and_b64 s[64:65], s[4:5], s[64:65]
	s_or_b64 s[14:15], s[14:15], s[16:17]
	s_or_b64 s[62:63], s[62:63], s[64:65]
	v_cmp_eq_f32_e64 s[64:65], v11, v0
	v_cndmask_b32_e64 v19, 0, 1, s[14:15]
	v_cmp_eq_f32_e64 s[14:15], v59, v0
	v_cmp_eq_f32_e64 s[16:17], v61, v0
	s_and_b64 s[80:81], s[4:5], s[64:65]
	v_cmp_gt_f32_e64 s[64:65], v10, v0
	s_and_b64 s[66:67], s[6:7], s[14:15]
	v_cmp_gt_f32_e64 s[14:15], v61, v0
	s_and_b64 s[16:17], s[6:7], s[16:17]
	v_cndmask_b32_e64 v36, 0, 1, s[64:65]
	v_cmp_gt_f32_e64 s[64:65], v5, v0
	s_or_b64 s[14:15], s[14:15], s[16:17]
	v_cndmask_b32_e64 v20, 0, 1, s[14:15]
	v_cndmask_b32_e64 v37, 0, 1, s[64:65]
	v_cmp_gt_f32_e64 s[64:65], v4, v0
	v_cmp_eq_f32_e64 s[14:15], v60, v0
	v_cmp_eq_f32_e64 s[16:17], v56, v0
	v_cndmask_b32_e64 v38, 0, 1, s[64:65]
	v_cmp_gt_f32_e64 s[64:65], v9, v0
	s_and_b64 s[68:69], s[6:7], s[14:15]
	v_cmp_gt_f32_e64 s[14:15], v56, v0
	s_and_b64 s[16:17], s[6:7], s[16:17]
	v_addc_co_u32_e64 v2, s[64:65], 0, v2, s[64:65]
	s_or_b64 s[14:15], s[14:15], s[16:17]
	v_cmp_gt_f32_e64 s[64:65], v8, v0
	v_cndmask_b32_e64 v21, 0, 1, s[14:15]
	v_cmp_eq_f32_e64 s[14:15], v54, v0
	v_cmp_eq_f32_e64 s[16:17], v16, v0
	v_addc_co_u32_e64 v2, s[64:65], v2, v36, s[64:65]
	s_and_b64 s[70:71], s[6:7], s[14:15]
	v_cmp_gt_f32_e64 s[14:15], v16, v0
	s_and_b64 s[16:17], s[6:7], s[16:17]
	v_cmp_gt_f32_e64 s[64:65], v6, v0
	s_or_b64 s[14:15], s[14:15], s[16:17]
	v_cmp_gt_f32_e64 s[22:23], v59, v0
	v_addc_co_u32_e64 v2, s[64:65], v2, v37, s[64:65]
	v_cndmask_b32_e64 v22, 0, 1, s[14:15]
	v_cmp_eq_f32_e64 s[14:15], v55, v0
	v_cmp_gt_f32_e64 s[64:65], v7, v0
	v_cmp_gt_f32_e64 s[24:25], v60, v0
	v_cmp_gt_f32_e64 s[26:27], v54, v0
	v_cmp_gt_f32_e64 s[28:29], v55, v0
	s_and_b64 s[72:73], s[6:7], s[14:15]
	v_cmp_gt_f32_e64 s[30:31], v50, v0
	v_cmp_eq_f32_e64 s[34:35], v50, v0
	v_cmp_gt_f32_e64 s[14:15], v51, v0
	v_cmp_eq_f32_e64 s[36:37], v51, v0
	v_cmp_gt_f32_e64 s[38:39], v44, v0
	v_cmp_eq_f32_e64 s[40:41], v44, v0
	v_cmp_gt_f32_e64 s[16:17], v42, v0
	v_cmp_eq_f32_e64 s[42:43], v42, v0
	v_cmp_gt_f32_e64 s[44:45], v45, v0
	v_cmp_eq_f32_e64 s[46:47], v45, v0
	v_cmp_gt_f32_e64 s[18:19], v43, v0
	v_cmp_eq_f32_e64 s[48:49], v43, v0
	v_cmp_gt_f32_e64 s[50:51], v29, v0
; DEVI void nsa_item(const Ctx& cx, const unsigned* cflag, int b, int g, int qt, unsigned char* lds, int wv) {
;     ...
;     for (int e = 0; e < 8; ++e) {
;       const int m = sub * 8 + e;
;       float raw = impA[tl2 * 33 + m] + (m > 0 ? impB[tl2 * 33 + m - 1] : 0.f);
;       bool valid = m <= cur, forced = (m == 0) | (m == cur) | (m == cur - 1);
;       const float am = valid ? (forced ? 1e9f : raw) : -1e30f;
;       int rank = 0;
; #pragma unroll
;       for (int j = 0; j < 32; ++j) rank += (a[j] > am || (a[j] == am && j < m)) ? 1 : 0;
;       if (rank < 16 && valid) bits |= 1u << m;
	v_cmp_eq_f32_e64 s[52:53], v29, v0
	v_cmp_gt_f32_e64 s[20:21], v27, v0
	v_cmp_eq_f32_e64 s[54:55], v27, v0
	v_cndmask_b32_e64 v23, 0, 1, s[56:57]
	v_cmp_gt_f32_e64 s[56:57], v17, v0
	v_cndmask_b32_e64 v30, 0, 1, s[58:59]
	v_cmp_gt_f32_e64 s[58:59], v26, v0
	v_cndmask_b32_e64 v31, 0, 1, s[60:61]
	v_cmp_gt_f32_e64 s[60:61], v13, v0
	v_cndmask_b32_e64 v18, 0, 1, s[62:63]
	v_cmp_gt_f32_e64 s[62:63], v11, v0
	v_addc_co_u32_e64 v0, s[64:65], v2, v38, s[64:65]
	s_or_b64 s[22:23], s[22:23], s[66:67]
	v_addc_co_u32_e64 v0, s[22:23], v0, v19, s[22:23]
	s_or_b64 s[22:23], s[24:25], s[68:69]
	s_nop 0
	v_addc_co_u32_e64 v0, s[22:23], v0, v20, s[22:23]
	s_or_b64 s[22:23], s[26:27], s[70:71]
	s_nop 0
	v_addc_co_u32_e64 v0, s[22:23], v0, v21, s[22:23]
	s_or_b64 s[22:23], s[28:29], s[72:73]
	s_nop 0
	v_addc_co_u32_e64 v0, s[22:23], v0, v22, s[22:23]
	s_and_b64 s[22:23], s[34:35], s[8:9]
	s_or_b64 s[22:23], s[30:31], s[22:23]
	v_cndmask_b32_e64 v2, 0, 1, s[22:23]
	s_and_b64 s[22:23], s[36:37], s[8:9]
	s_and_b64 s[24:25], s[40:41], s[8:9]
	s_or_b64 s[24:25], s[38:39], s[24:25]
	s_or_b64 s[14:15], s[14:15], s[22:23]
	v_cndmask_b32_e64 v19, 0, 1, s[24:25]
	s_and_b64 s[24:25], s[42:43], s[8:9]
	s_and_b64 s[26:27], s[46:47], s[8:9]
	v_addc_co_u32_e64 v0, s[14:15], v0, v2, s[14:15]
	s_or_b64 s[26:27], s[44:45], s[26:27]
	s_or_b64 s[14:15], s[16:17], s[24:25]
	v_cndmask_b32_e64 v20, 0, 1, s[26:27]
	s_and_b64 s[26:27], s[48:49], s[8:9]
	s_and_b64 s[28:29], s[52:53], s[8:9]
	v_addc_co_u32_e64 v0, s[14:15], v0, v19, s[14:15]
	s_or_b64 s[28:29], s[50:51], s[28:29]
	s_or_b64 s[14:15], s[18:19], s[26:27]
	v_cndmask_b32_e64 v21, 0, 1, s[28:29]
	s_and_b64 s[28:29], s[54:55], s[8:9]
	v_addc_co_u32_e64 v0, s[14:15], v0, v20, s[14:15]
	s_or_b64 s[14:15], s[20:21], s[28:29]
	s_nop 0
	v_addc_co_u32_e64 v0, s[14:15], v0, v21, s[14:15]
	s_or_b64 s[14:15], s[56:57], s[74:75]
	s_nop 0
	v_addc_co_u32_e64 v0, s[14:15], v0, v23, s[14:15]
	s_or_b64 s[14:15], s[58:59], s[76:77]
	s_nop 0
	v_addc_co_u32_e64 v0, s[14:15], v0, v30, s[14:15]
	s_or_b64 s[14:15], s[60:61], s[78:79]
	s_nop 0
	v_addc_co_u32_e64 v19, s[14:15], v0, v31, s[14:15]
	v_or_b32_e32 v0, 2, v66
	v_cmp_eq_u32_e64 s[14:15], v0, v68
	v_cmp_eq_u32_e64 s[18:19], v0, v69
	s_or_b64 s[14:15], s[14:15], s[18:19]
	v_cndmask_b32_e64 v1, v1, v239, s[14:15]
	v_cmp_le_i32_e64 s[14:15], v0, v68
	v_cmp_lt_u32_e64 s[58:59], 17, v0
	s_or_b64 s[16:17], s[62:63], s[80:81]
	v_cndmask_b32_e64 v1, v238, v1, s[14:15]
	v_cmp_ge_f32_e64 s[18:19], v58, v1
	v_cmp_eq_f32_e64 s[20:21], v59, v1
	s_and_b64 s[20:21], s[6:7], s[20:21]
	v_cndmask_b32_e64 v2, 0, 1, s[18:19]
	v_cmp_ge_f32_e64 s[18:19], v67, v1
	v_cmp_eq_f32_e64 s[56:57], v25, v1
	s_and_b64 s[74:75], s[56:57], s[58:59]
	v_addc_co_u32_e64 v2, s[18:19], 0, v2, s[18:19]
	v_cmp_gt_f32_e64 s[18:19], v59, v1
	s_or_b64 s[18:19], s[18:19], s[20:21]
	v_cmp_eq_f32_e64 s[20:21], v61, v1
	s_and_b64 s[22:23], s[6:7], s[20:21]
	v_cmp_gt_f32_e64 s[20:21], v10, v1
	v_cmp_eq_f32_e64 s[58:59], v17, v1
	v_cndmask_b32_e64 v3, 0, 1, s[18:19]
	v_cndmask_b32_e64 v20, 0, 1, s[20:21]
	v_cmp_gt_f32_e64 s[20:21], v5, v1
	v_cmp_gt_f32_e64 s[18:19], v61, v1
	v_cmp_gt_f32_e64 s[56:57], v17, v1
	v_cndmask_b32_e64 v21, 0, 1, s[20:21]
	v_cmp_gt_f32_e64 s[20:21], v4, v1
	s_and_b64 s[58:59], s[4:5], s[58:59]
	s_or_b64 s[18:19], s[18:19], s[22:23]
	v_cndmask_b32_e64 v22, 0, 1, s[20:21]
	v_cmp_gt_f32_e64 s[20:21], v8, v1
	v_cmp_eq_f32_e64 s[22:23], v60, v1
	s_or_b64 s[56:57], s[56:57], s[58:59]
	v_addc_co_u32_e64 v2, s[20:21], v2, v20, s[20:21]
	v_cmp_gt_f32_e64 s[20:21], v6, v1
	v_cmp_eq_f32_e64 s[58:59], v28, v1
	v_cmp_eq_f32_e64 s[60:61], v26, v1
	v_addc_co_u32_e64 v2, s[20:21], v2, v21, s[20:21]
	v_cmp_gt_f32_e64 s[20:21], v7, v1
	s_and_b64 s[22:23], s[6:7], s[22:23]
	s_and_b64 s[76:77], s[4:5], s[58:59]
	v_addc_co_u32_e64 v2, s[20:21], v2, v22, s[20:21]
	v_cmp_gt_f32_e64 s[20:21], v60, v1
	v_cmp_gt_f32_e64 s[58:59], v26, v1
	s_and_b64 s[60:61], s[4:5], s[60:61]
	s_or_b64 s[20:21], s[20:21], s[22:23]
	v_cmp_eq_f32_e64 s[22:23], v56, v1
	v_cmp_lt_u32_e64 s[24:25], 5, v0
	s_or_b64 s[58:59], s[58:59], s[60:61]
	v_cmp_eq_f32_e64 s[60:61], v24, v1
	v_cmp_lt_u32_e64 s[62:63], 21, v0
	s_and_b64 s[66:67], s[22:23], s[24:25]
	v_cmp_eq_f32_e64 s[24:25], v54, v1
	s_and_b64 s[78:79], s[60:61], s[62:63]
	v_cmp_eq_f32_e64 s[62:63], v13, v1
	v_cmp_gt_f32_e64 s[22:23], v54, v1
	s_and_b64 s[24:25], s[6:7], s[24:25]
	v_cmp_gt_f32_e64 s[60:61], v13, v1
	s_and_b64 s[62:63], s[4:5], s[62:63]
	s_or_b64 s[22:23], s[22:23], s[24:25]
	v_cmp_eq_f32_e64 s[24:25], v16, v1
	v_cmp_eq_f32_e64 s[26:27], v55, v1
	s_or_b64 s[60:61], s[60:61], s[62:63]
	v_cmp_eq_f32_e64 s[62:63], v12, v1
	v_cmp_eq_f32_e64 s[64:65], v11, v1
	s_and_b64 s[68:69], s[6:7], s[24:25]
	v_cmp_gt_f32_e64 s[24:25], v55, v1
	s_and_b64 s[26:27], s[6:7], s[26:27]
	s_and_b64 s[80:81], s[4:5], s[62:63]
	v_cmp_gt_f32_e64 s[62:63], v11, v1
	s_and_b64 s[64:65], s[4:5], s[64:65]
	s_or_b64 s[24:25], s[24:25], s[26:27]
	v_cmp_eq_f32_e64 s[26:27], v50, v1
	v_cmp_lt_u32_e64 s[28:29], 9, v0
	v_cmp_eq_f32_e64 s[42:43], v45, v1
	v_cmp_lt_u32_e64 s[44:45], 13, v0
	s_or_b64 s[62:63], s[62:63], s[64:65]
	v_cndmask_b32_e64 v21, 0, 1, s[20:21]
	v_cmp_gt_f32_e64 s[20:21], v56, v1
	v_cndmask_b32_e64 v22, 0, 1, s[22:23]
	v_cmp_gt_f32_e64 s[22:23], v16, v1
	v_cndmask_b32_e64 v23, 0, 1, s[24:25]
	v_cmp_gt_f32_e64 s[24:25], v50, v1
	s_and_b64 s[70:71], s[26:27], s[28:29]
	v_cmp_gt_f32_e64 s[26:27], v51, v1
	v_cmp_eq_f32_e64 s[28:29], v51, v1
	v_cmp_gt_f32_e64 s[30:31], v44, v1
	v_cmp_eq_f32_e64 s[34:35], v44, v1
	v_cmp_gt_f32_e64 s[36:37], v42, v1
	v_cmp_eq_f32_e64 s[38:39], v42, v1
	v_cmp_gt_f32_e64 s[40:41], v45, v1
; DEVI void nsa_item(const Ctx& cx, const unsigned* cflag, int b, int g, int qt, unsigned char* lds, int wv) {
;     ...
;     for (int e = 0; e < 8; ++e) {
;       const int m = sub * 8 + e;
;       float raw = impA[tl2 * 33 + m] + (m > 0 ? impB[tl2 * 33 + m - 1] : 0.f);
;       bool valid = m <= cur, forced = (m == 0) | (m == cur) | (m == cur - 1);
;       const float am = valid ? (forced ? 1e9f : raw) : -1e30f;
;       int rank = 0;
; #pragma unroll
;       for (int j = 0; j < 32; ++j) rank += (a[j] > am || (a[j] == am && j < m)) ? 1 : 0;
;       if (rank < 16 && valid) bits |= 1u << m;
	s_and_b64 s[72:73], s[42:43], s[44:45]
	v_cmp_gt_f32_e64 s[42:43], v43, v1
	v_cmp_eq_f32_e64 s[44:45], v43, v1
	v_cmp_gt_f32_e64 s[46:47], v29, v1
	v_cmp_eq_f32_e64 s[48:49], v29, v1
	v_cmp_gt_f32_e64 s[50:51], v27, v1
	v_cmp_eq_f32_e64 s[52:53], v27, v1
	v_cmp_gt_f32_e64 s[54:55], v25, v1
	v_cndmask_b32_e64 v30, 0, 1, s[56:57]
	v_cmp_gt_f32_e64 s[56:57], v28, v1
	v_cndmask_b32_e64 v31, 0, 1, s[58:59]
	v_cmp_gt_f32_e64 s[58:59], v24, v1
	v_cndmask_b32_e64 v0, 0, 1, s[60:61]
	v_cmp_gt_f32_e64 s[60:61], v12, v1
	v_cndmask_b32_e64 v20, 0, 1, s[62:63]
	v_cmp_gt_f32_e64 s[62:63], v9, v1
	v_cmp_eq_f32_e64 s[64:65], v9, v1
	v_addc_co_u32_e64 v1, s[18:19], v2, v3, s[18:19]
	s_or_b64 s[18:19], s[20:21], s[66:67]
	s_nop 0
	v_addc_co_u32_e64 v1, s[18:19], v1, v21, s[18:19]
	s_or_b64 s[18:19], s[22:23], s[68:69]
	s_nop 0
	v_addc_co_u32_e64 v1, s[18:19], v1, v22, s[18:19]
	s_or_b64 s[18:19], s[24:25], s[70:71]
	s_nop 0
	v_addc_co_u32_e64 v1, s[18:19], v1, v23, s[18:19]
	s_and_b64 s[18:19], s[28:29], s[8:9]
	s_or_b64 s[18:19], s[26:27], s[18:19]
	v_cndmask_b32_e64 v2, 0, 1, s[18:19]
	s_and_b64 s[18:19], s[34:35], s[8:9]
	s_and_b64 s[20:21], s[38:39], s[8:9]
	s_or_b64 s[20:21], s[36:37], s[20:21]
	s_or_b64 s[18:19], s[30:31], s[18:19]
	v_cndmask_b32_e64 v3, 0, 1, s[20:21]
	s_and_b64 s[20:21], s[44:45], s[8:9]
	v_addc_co_u32_e64 v1, s[18:19], v1, v2, s[18:19]
	s_or_b64 s[20:21], s[42:43], s[20:21]
	s_or_b64 s[18:19], s[40:41], s[72:73]
	v_cndmask_b32_e64 v21, 0, 1, s[20:21]
	s_and_b64 s[20:21], s[48:49], s[8:9]
	v_addc_co_u32_e64 v1, s[18:19], v1, v3, s[18:19]
	s_and_b64 s[22:23], s[52:53], s[8:9]
	s_or_b64 s[18:19], s[46:47], s[20:21]
	s_or_b64 s[22:23], s[50:51], s[22:23]
	v_addc_co_u32_e64 v1, s[18:19], v1, v21, s[18:19]
	v_cndmask_b32_e64 v22, 0, 1, s[22:23]
	s_or_b64 s[18:19], s[54:55], s[74:75]
	v_addc_co_u32_e64 v1, s[18:19], v1, v22, s[18:19]
	s_or_b64 s[18:19], s[56:57], s[76:77]
	s_nop 0
	v_addc_co_u32_e64 v1, s[18:19], v1, v30, s[18:19]
	s_or_b64 s[18:19], s[58:59], s[78:79]
	s_nop 0
	v_addc_co_u32_e64 v1, s[18:19], v1, v31, s[18:19]
	s_or_b64 s[18:19], s[60:61], s[80:81]
	s_nop 0
	v_addc_co_u32_e64 v21, s[18:19], v1, v0, s[18:19]
	v_add_u32_e32 v0, 0xb00c, v71
	ds_read_b32 v34, v71 offset:45076
	ds_read_b32 v35, v71 offset:61968
	v_add_u32_e32 v1, 0xf208, v71
	ds_read2_b32 v[22:23], v0 offset1:1
	ds_read2_b32 v[30:31], v1 offset1:1
	v_or_b32_e32 v36, 3, v66
	v_cmp_eq_u32_e64 s[20:21], v36, v68
	v_cmp_eq_u32_e64 s[22:23], v36, v69
	s_or_b64 s[20:21], s[20:21], s[22:23]
	s_waitcnt lgkmcnt(0)
	v_add_f32_e32 v22, v22, v30
	v_cndmask_b32_e64 v22, v22, v239, s[20:21]
	v_cmp_le_i32_e64 s[20:21], v36, v68
	v_cmp_lt_u32_e64 s[48:49], 16, v36
	v_cmp_lt_u32_e64 s[50:51], 17, v36
	v_cndmask_b32_e64 v30, v238, v22, s[20:21]
	v_cmp_eq_f32_e64 s[46:47], v27, v30
	s_and_b64 s[72:73], s[46:47], s[48:49]
	v_cmp_eq_f32_e64 s[48:49], v25, v30
	v_cmp_gt_f32_e64 s[46:47], v25, v30
	s_and_b64 s[48:49], s[48:49], s[50:51]
	v_cmp_ge_f32_e64 s[22:23], v58, v30
	s_or_b64 s[46:47], s[46:47], s[48:49]
	v_cmp_eq_f32_e64 s[48:49], v17, v30
	v_cmp_lt_u32_e64 s[50:51], 18, v36
	v_cndmask_b32_e64 v22, 0, 1, s[22:23]
	v_cmp_ge_f32_e64 s[22:23], v67, v30
	s_and_b64 s[74:75], s[48:49], s[50:51]
	v_cmp_eq_f32_e64 s[50:51], v28, v30
	v_addc_co_u32_e64 v37, s[22:23], 0, v22, s[22:23]
	v_cmp_gt_f32_e64 s[48:49], v28, v30
	s_and_b64 s[50:51], s[4:5], s[50:51]
	v_cmp_ge_f32_e64 s[22:23], v59, v30
	v_cmp_eq_f32_e64 s[24:25], v61, v30
	s_or_b64 s[48:49], s[48:49], s[50:51]
	v_cmp_eq_f32_e64 s[50:51], v26, v30
	v_cmp_lt_u32_e64 s[52:53], 20, v36
	v_cndmask_b32_e64 v39, 0, 1, s[22:23]
	v_cmp_gt_f32_e64 s[22:23], v61, v30
	s_and_b64 s[24:25], s[6:7], s[24:25]
	s_and_b64 s[76:77], s[50:51], s[52:53]
	v_cmp_eq_f32_e64 s[52:53], v24, v30
	v_cmp_lt_u32_e64 s[54:55], 21, v36
	s_or_b64 s[22:23], s[22:23], s[24:25]
	v_cmp_eq_f32_e64 s[24:25], v60, v30
	v_cmp_lt_u32_e64 s[26:27], 4, v36
	v_cmp_gt_f32_e64 s[50:51], v24, v30
	s_and_b64 s[52:53], s[52:53], s[54:55]
	s_and_b64 s[60:61], s[24:25], s[26:27]
	v_cmp_eq_f32_e64 s[26:27], v56, v30
	v_cmp_lt_u32_e64 s[28:29], 5, v36
	s_or_b64 s[50:51], s[50:51], s[52:53]
	v_cmp_eq_f32_e64 s[52:53], v13, v30
	v_cmp_lt_u32_e64 s[54:55], 22, v36
	v_cmp_gt_f32_e64 s[24:25], v56, v30
	s_and_b64 s[26:27], s[26:27], s[28:29]
	s_and_b64 s[78:79], s[52:53], s[54:55]
	v_cmp_eq_f32_e64 s[54:55], v12, v30
	s_and_b64 s[64:65], s[4:5], s[64:65]
	s_or_b64 s[24:25], s[24:25], s[26:27]
	v_cmp_eq_f32_e64 s[26:27], v54, v30
	v_cmp_lt_u32_e64 s[28:29], 6, v36
	v_cmp_gt_f32_e64 s[52:53], v12, v30
	s_and_b64 s[54:55], s[4:5], s[54:55]
	s_or_b64 s[18:19], s[62:63], s[64:65]
	s_and_b64 s[62:63], s[26:27], s[28:29]
	v_cmp_eq_f32_e64 s[28:29], v16, v30
	s_or_b64 s[52:53], s[52:53], s[54:55]
	v_cmp_eq_f32_e64 s[54:55], v11, v30
	v_cmp_lt_u32_e64 s[56:57], 24, v36
	v_cmp_gt_f32_e64 s[26:27], v16, v30
	s_and_b64 s[28:29], s[6:7], s[28:29]
	s_and_b64 s[80:81], s[54:55], s[56:57]
	v_cmp_eq_f32_e64 s[56:57], v9, v30
	v_cmp_lt_u32_e64 s[58:59], 25, v36
	s_or_b64 s[26:27], s[26:27], s[28:29]
	v_cmp_eq_f32_e64 s[28:29], v55, v30
	v_cmp_lt_u32_e64 s[30:31], 8, v36
	v_cmp_gt_f32_e64 s[54:55], v9, v30
	s_and_b64 s[56:57], s[56:57], s[58:59]
	s_and_b64 s[64:65], s[28:29], s[30:31]
	v_cmp_eq_f32_e64 s[30:31], v50, v30
	v_cmp_lt_u32_e64 s[34:35], 9, v36
	v_cmp_eq_f32_e64 s[38:39], v42, v30
	v_cmp_lt_u32_e64 s[40:41], 12, v36
	s_or_b64 s[54:55], s[54:55], s[56:57]
	v_cmp_eq_f32_e64 s[56:57], v10, v30
	v_cmp_gt_f32_e64 s[28:29], v50, v30
	s_and_b64 s[30:31], s[30:31], s[34:35]
	s_and_b64 s[66:67], s[38:39], s[40:41]
	v_cmp_eq_f32_e64 s[40:41], v45, v30
	v_cmp_lt_u32_e64 s[42:43], 13, v36
; DEVI void nsa_item(const Ctx& cx, const unsigned* cflag, int b, int g, int qt, unsigned char* lds, int wv) {
;     ...
;     for (int e = 0; e < 8; ++e) {
;       const int m = sub * 8 + e;
;       float raw = impA[tl2 * 33 + m] + (m > 0 ? impB[tl2 * 33 + m - 1] : 0.f);
;       bool valid = m <= cur, forced = (m == 0) | (m == cur) | (m == cur - 1);
;       const float am = valid ? (forced ? 1e9f : raw) : -1e30f;
;       int rank = 0;
; #pragma unroll
;       for (int j = 0; j < 32; ++j) rank += (a[j] > am || (a[j] == am && j < m)) ? 1 : 0;
;       if (rank < 16 && valid) bits |= 1u << m;
	s_and_b64 s[58:59], s[4:5], s[56:57]
	v_cmp_gt_f32_e64 s[56:57], v5, v30
	s_or_b64 s[28:29], s[28:29], s[30:31]
	v_cmp_lt_u32_e64 s[30:31], 10, v36
	s_and_b64 s[40:41], s[40:41], s[42:43]
	v_cmp_lt_u32_e64 s[42:43], 14, v36
	v_cndmask_b32_e64 v36, 0, 1, s[56:57]
	v_cmp_gt_f32_e64 s[56:57], v4, v30
	v_cmp_gt_f32_e64 s[38:39], v45, v30
	v_cndmask_b32_e64 v40, 0, 1, s[22:23]
	v_cndmask_b32_e64 v62, 0, 1, s[56:57]
	v_cmp_gt_f32_e64 s[56:57], v8, v30
	v_cmp_gt_f32_e64 s[22:23], v60, v30
	v_cndmask_b32_e64 v47, 0, 1, s[28:29]
	v_addc_co_u32_e64 v37, s[56:57], v37, v39, s[56:57]
	v_cmp_gt_f32_e64 s[56:57], v6, v30
	v_cmp_eq_f32_e64 s[28:29], v51, v30
	s_or_b64 s[38:39], s[38:39], s[40:41]
	v_addc_co_u32_e64 v36, s[56:57], v37, v36, s[56:57]
	v_cmp_eq_f32_e64 s[40:41], v43, v30
	v_cmp_gt_f32_e64 s[56:57], v7, v30
	v_cndmask_b32_e64 v41, 0, 1, s[24:25]
	v_cmp_gt_f32_e64 s[24:25], v54, v30
	v_cndmask_b32_e64 v46, 0, 1, s[26:27]
	v_cmp_gt_f32_e64 s[26:27], v55, v30
	v_cmp_gt_f32_e64 s[36:37], v51, v30
	s_and_b64 s[68:69], s[28:29], s[30:31]
	v_cmp_gt_f32_e64 s[30:31], v44, v30
	v_cmp_eq_f32_e64 s[34:35], v44, v30
	v_cmp_gt_f32_e64 s[28:29], v42, v30
	v_cndmask_b32_e64 v48, 0, 1, s[38:39]
	v_cmp_gt_f32_e64 s[38:39], v43, v30
	s_and_b64 s[70:71], s[40:41], s[42:43]
	v_cmp_gt_f32_e64 s[40:41], v29, v30
	v_cmp_eq_f32_e64 s[42:43], v29, v30
	v_cmp_gt_f32_e64 s[44:45], v27, v30
	v_cndmask_b32_e64 v49, 0, 1, s[46:47]
	v_cmp_gt_f32_e64 s[46:47], v17, v30
	v_cndmask_b32_e64 v52, 0, 1, s[48:49]
	v_cmp_gt_f32_e64 s[48:49], v26, v30
	v_cndmask_b32_e64 v53, 0, 1, s[50:51]
	v_cmp_gt_f32_e64 s[50:51], v13, v30
	v_cndmask_b32_e64 v57, 0, 1, s[52:53]
	v_cmp_gt_f32_e64 s[52:53], v11, v30
	v_cndmask_b32_e64 v22, 0, 1, s[54:55]
	v_cmp_gt_f32_e64 s[54:55], v10, v30
	v_addc_co_u32_e64 v30, s[56:57], v36, v62, s[56:57]
	s_or_b64 s[22:23], s[22:23], s[60:61]
	v_addc_co_u32_e64 v30, s[22:23], v30, v40, s[22:23]
	s_or_b64 s[22:23], s[24:25], s[62:63]
	s_nop 0
	v_addc_co_u32_e64 v30, s[22:23], v30, v41, s[22:23]
	s_or_b64 s[22:23], s[26:27], s[64:65]
	s_nop 0
	v_addc_co_u32_e64 v30, s[22:23], v30, v46, s[22:23]
	s_or_b64 s[22:23], s[36:37], s[68:69]
	s_nop 0
	v_addc_co_u32_e64 v30, s[22:23], v30, v47, s[22:23]
	s_and_b64 s[22:23], s[34:35], s[8:9]
	s_or_b64 s[22:23], s[30:31], s[22:23]
	v_cndmask_b32_e64 v36, 0, 1, s[22:23]
	s_and_b64 s[22:23], s[42:43], s[8:9]
	s_or_b64 s[22:23], s[40:41], s[22:23]
	v_cndmask_b32_e64 v37, 0, 1, s[22:23]
	s_or_b64 s[22:23], s[28:29], s[66:67]
	v_addc_co_u32_e64 v30, s[22:23], v30, v36, s[22:23]
	s_or_b64 s[22:23], s[38:39], s[70:71]
	s_nop 0
	v_addc_co_u32_e64 v30, s[22:23], v30, v48, s[22:23]
	s_or_b64 s[22:23], s[44:45], s[72:73]
	s_nop 0
	v_addc_co_u32_e64 v30, s[22:23], v30, v37, s[22:23]
	s_or_b64 s[22:23], s[46:47], s[74:75]
	s_nop 0
	v_addc_co_u32_e64 v30, s[22:23], v30, v49, s[22:23]
	s_or_b64 s[22:23], s[48:49], s[76:77]
	s_nop 0
	v_addc_co_u32_e64 v30, s[22:23], v30, v52, s[22:23]
	s_or_b64 s[22:23], s[50:51], s[78:79]
	s_nop 0
	v_addc_co_u32_e64 v30, s[22:23], v30, v53, s[22:23]
	s_or_b64 s[22:23], s[52:53], s[80:81]
	s_nop 0
	v_addc_co_u32_e64 v30, s[22:23], v30, v57, s[22:23]
	v_or_b32_e32 v49, 4, v66
	v_cmp_eq_u32_e64 s[22:23], v49, v68
	v_cmp_eq_u32_e64 s[26:27], v49, v69
	v_add_f32_e32 v23, v23, v31
	s_or_b64 s[22:23], s[22:23], s[26:27]
	v_cndmask_b32_e64 v23, v23, v239, s[22:23]
	v_cmp_le_i32_e64 s[22:23], v49, v68
	v_cmp_lt_u32_e64 s[36:37], 6, v49
	v_cmp_lt_u32_e64 s[38:39], 9, v49
	v_cndmask_b32_e64 v53, v238, v23, s[22:23]
	v_cmp_ge_f32_e64 s[26:27], v58, v53
	v_cmp_eq_f32_e64 s[28:29], v60, v53
	v_cmp_eq_f32_e64 s[30:31], v16, v53
	v_cndmask_b32_e64 v57, 0, 1, s[26:27]
	v_cmp_ge_f32_e64 s[26:27], v61, v53
	s_and_b64 s[34:35], s[6:7], s[28:29]
	v_cmp_gt_f32_e64 s[28:29], v16, v53
	v_cndmask_b32_e64 v31, 0, 1, s[26:27]
	v_cmp_gt_f32_e64 s[26:27], v60, v53
	s_and_b64 s[30:31], s[6:7], s[30:31]
	s_or_b64 s[28:29], s[28:29], s[30:31]
	s_or_b64 s[26:27], s[26:27], s[34:35]
	v_cmp_eq_f32_e64 s[30:31], v56, v53
	v_cmp_lt_u32_e64 s[34:35], 5, v49
	s_and_b64 s[40:41], s[30:31], s[34:35]
	v_cmp_eq_f32_e64 s[34:35], v54, v53
	s_and_b64 s[42:43], s[34:35], s[36:37]
	v_cmp_eq_f32_e64 s[36:37], v50, v53
	v_cmp_gt_f32_e64 s[34:35], v50, v53
	s_and_b64 s[36:37], s[36:37], s[38:39]
	s_or_b64 s[34:35], s[34:35], s[36:37]
	v_cndmask_b32_e64 v37, 0, 1, s[34:35]
	v_cmp_gt_f32_e64 s[34:35], v4, v53
	v_cndmask_b32_e64 v23, 0, 1, s[28:29]
	v_cmp_ge_f32_e64 s[28:29], v59, v53
	v_cndmask_b32_e64 v36, 0, 1, s[34:35]
	v_cmp_gt_f32_e64 s[34:35], v7, v53
	v_addc_co_u32_e64 v31, s[28:29], 0, v31, s[28:29]
	s_nop 0
	v_cndmask_b32_e64 v39, 0, 1, s[34:35]
	v_cmp_gt_f32_e64 s[28:29], v56, v53
	v_lshlrev_b16_e32 v36, 2, v36
	v_lshlrev_b16_e32 v39, 3, v39
	v_cmp_gt_f32_e64 s[34:35], v6, v53
	v_cmp_eq_f32_e64 s[36:37], v51, v53
	v_cmp_lt_u32_e64 s[38:39], 10, v49
	v_cmp_gt_f32_e64 s[30:31], v54, v53
	v_or_b32_e32 v36, v39, v36
	v_cndmask_b32_e64 v39, 0, 1, s[34:35]
	v_cmp_gt_f32_e64 s[34:35], v5, v53
	s_or_b64 s[28:29], s[28:29], s[40:41]
	s_and_b64 s[46:47], s[36:37], s[38:39]
	v_cmp_eq_f32_e64 s[38:39], v44, v53
	v_cmp_lt_u32_e64 s[40:41], 11, v49
	v_lshlrev_b16_e32 v39, 1, v39
	v_cndmask_b32_e64 v40, 0, 1, s[34:35]
	s_or_b64 s[30:31], s[30:31], s[42:43]
	v_cmp_gt_f32_e64 s[36:37], v44, v53
	s_and_b64 s[38:39], s[38:39], s[40:41]
	v_cmp_eq_f32_e64 s[42:43], v45, v53
	v_cmp_lt_u32_e64 s[44:45], 13, v49
	v_or_b32_e32 v39, v40, v39
	s_or_b64 s[36:37], s[36:37], s[38:39]
	v_cmp_eq_f32_e64 s[38:39], v42, v53
	v_cmp_gt_f32_e64 s[40:41], v45, v53
	s_and_b64 s[42:43], s[42:43], s[44:45]
	v_bitop3_b16 v36, v39, v36, 3 bitop3:0xec
	v_cndmask_b32_e64 v39, 0, 1, s[36:37]
; DEVI void nsa_item(const Ctx& cx, const unsigned* cflag, int b, int g, int qt, unsigned char* lds, int wv) {
;     ...
;     for (int e = 0; e < 8; ++e) {
;       const int m = sub * 8 + e;
;       float raw = impA[tl2 * 33 + m] + (m > 0 ? impB[tl2 * 33 + m - 1] : 0.f);
;       bool valid = m <= cur, forced = (m == 0) | (m == cur) | (m == cur - 1);
;       const float am = valid ? (forced ? 1e9f : raw) : -1e30f;
;       int rank = 0;
; #pragma unroll
;       for (int j = 0; j < 32; ++j) rank += (a[j] > am || (a[j] == am && j < m)) ? 1 : 0;
;       if (rank < 16 && valid) bits |= 1u << m;
	v_cmp_gt_f32_e64 s[36:37], v42, v53
	s_or_b64 s[40:41], s[40:41], s[42:43]
	s_and_b64 s[38:39], s[38:39], s[8:9]
	v_cndmask_b32_e64 v40, 0, 1, s[40:41]
	s_or_b64 s[36:37], s[36:37], s[38:39]
	v_cmp_eq_f32_e64 s[38:39], v43, v53
	v_cmp_lt_u32_e64 s[40:41], 14, v49
	s_or_b64 s[24:25], s[54:55], s[58:59]
	s_and_b64 s[54:55], s[38:39], s[40:41]
	v_cmp_eq_f32_e64 s[40:41], v29, v53
	v_cmp_gt_f32_e64 s[38:39], v29, v53
	s_and_b64 s[40:41], s[40:41], s[8:9]
	v_cmp_eq_f32_e64 s[34:35], v55, v53
	v_cmp_eq_f32_e64 s[44:45], v27, v53
	s_or_b64 s[38:39], s[38:39], s[40:41]
	s_and_b64 s[52:53], s[6:7], s[34:35]
	v_cmp_gt_f32_e64 s[34:35], v51, v53
	v_cmp_gt_f32_e64 s[42:43], v27, v53
	v_cmp_eq_f32_e64 s[48:49], v25, v53
	v_cmp_lt_u32_e64 s[50:51], 17, v49
	v_cndmask_b32_e64 v41, 0, 1, s[38:39]
	s_and_b64 s[38:39], s[44:45], s[8:9]
	s_or_b64 s[34:35], s[34:35], s[46:47]
	v_cmp_gt_f32_e64 s[46:47], v25, v53
	s_and_b64 s[48:49], s[48:49], s[50:51]
	s_or_b64 s[38:39], s[42:43], s[38:39]
	v_cmp_eq_f32_e64 s[40:41], v17, v53
	v_cmp_lt_u32_e64 s[42:43], 18, v49
	s_or_b64 s[46:47], s[46:47], s[48:49]
	s_and_b64 s[48:49], s[40:41], s[42:43]
	v_cmp_eq_f32_e64 s[42:43], v28, v53
	v_cmp_lt_u32_e64 s[44:45], 19, v49
	v_cmp_gt_f32_e64 s[40:41], v28, v53
	s_and_b64 s[42:43], s[42:43], s[44:45]
	s_or_b64 s[40:41], s[40:41], s[42:43]
	v_cmp_eq_f32_e64 s[42:43], v24, v53
	v_cmp_lt_u32_e64 s[44:45], 21, v49
	v_cndmask_b32_e64 v46, 0, 1, s[46:47]
	s_and_b64 s[50:51], s[42:43], s[44:45]
	v_cmp_eq_f32_e64 s[44:45], v13, v53
	v_cmp_lt_u32_e64 s[46:47], 22, v49
	v_cmp_gt_f32_e64 s[42:43], v13, v53
	s_and_b64 s[44:45], s[44:45], s[46:47]
	v_cndmask_b32_e64 v47, 0, 1, s[40:41]
	v_cmp_gt_f32_e64 s[40:41], v24, v53
	s_or_b64 s[42:43], s[42:43], s[44:45]
	v_cndmask_b32_e64 v48, 0, 1, s[42:43]
	s_or_b64 s[40:41], s[40:41], s[50:51]
	v_addc_co_u32_e64 v48, s[40:41], 0, v48, s[40:41]
	v_cmp_eq_f32_e64 s[42:43], v26, v53
	v_cmp_gt_f32_e64 s[40:41], v26, v53
	s_and_b64 s[42:43], s[4:5], s[42:43]
	s_or_b64 s[40:41], s[40:41], s[42:43]
	v_cmp_eq_f32_e64 s[42:43], v12, v53
	v_cmp_eq_f32_e64 s[44:45], v11, v53
	v_addc_co_u32_e64 v40, s[36:37], 0, v40, s[36:37]
	v_addc_co_u32_e64 v46, s[38:39], 0, v46, s[38:39]
	s_and_b64 s[50:51], s[4:5], s[42:43]
	v_cmp_gt_f32_e64 s[42:43], v11, v53
	s_and_b64 s[44:45], s[4:5], s[44:45]
	v_cmp_gt_f32_e64 s[36:37], v43, v53
	v_cmp_gt_f32_e64 s[38:39], v17, v53
	s_or_b64 s[42:43], s[42:43], s[44:45]
	v_cmp_eq_f32_e64 s[44:45], v9, v53
	v_cmp_lt_u32_e64 s[46:47], 25, v49
	v_addc_co_u32_e64 v37, s[30:31], 0, v37, s[30:31]
	s_or_b64 s[36:37], s[36:37], s[54:55]
	s_or_b64 s[38:39], s[38:39], s[48:49]
	s_and_b64 s[54:55], s[44:45], s[46:47]
	v_cmp_eq_f32_e64 s[46:47], v10, v53
	v_cmp_lt_u32_e64 s[48:49], 26, v49
	v_cmp_gt_f32_e64 s[30:31], v55, v53
	v_cmp_gt_f32_e64 s[44:45], v10, v53
	s_and_b64 s[46:47], s[46:47], s[48:49]
	v_cndmask_b32_e64 v62, 0, 1, s[40:41]
	s_or_b64 s[44:45], s[44:45], s[46:47]
	s_or_b64 s[30:31], s[30:31], s[52:53]
	v_cmp_gt_f32_e64 s[40:41], v12, v53
	v_cndmask_b32_e64 v52, 0, 1, s[44:45]
	v_cmp_ge_f32_e64 s[44:45], v67, v53
	v_addc_co_u32_e64 v49, s[30:31], 0, v62, s[30:31]
	v_cndmask_b32_e64 v63, 0, 1, s[42:43]
	v_addc_co_u32_e64 v57, s[44:45], 0, v57, s[44:45]
	v_cmp_eq_f32_e64 s[46:47], v8, v53
	s_or_b64 s[30:31], s[40:41], s[50:51]
	v_cmp_gt_f32_e64 s[42:43], v9, v53
	v_cmp_gt_f32_e64 s[44:45], v8, v53
	s_and_b64 s[46:47], s[4:5], s[46:47]
	v_addc_co_u32_e64 v53, s[30:31], 0, v63, s[30:31]
	v_or_b32_e32 v71, 5, v66
	s_or_b64 s[40:41], s[44:45], s[46:47]
	v_cmp_eq_u32_e64 s[30:31], v71, v68
	v_cmp_eq_u32_e64 s[44:45], v71, v69
	v_add_f32_e32 v34, v34, v35
	s_or_b64 s[30:31], s[30:31], s[44:45]
	v_or_b32_e32 v38, 6, v66
	v_cndmask_b32_e64 v34, v34, v239, s[30:31]
	v_cmp_le_i32_e64 s[30:31], v71, v68
	v_lshl_add_u32 v0, v38, 2, v70
	v_cmp_lt_u32_e64 s[48:49], 6, v71
	v_cndmask_b32_e64 v70, v238, v34, s[30:31]
	v_cmp_ge_f32_e64 s[44:45], v58, v70
	v_cmp_eq_f32_e64 s[46:47], v56, v70
	s_and_b64 s[46:47], s[6:7], s[46:47]
	v_cndmask_b32_e64 v34, 0, 1, s[44:45]
	v_cmp_ge_f32_e64 s[44:45], v67, v70
	v_cmp_lt_u32_e64 s[50:51], 8, v71
	v_cmp_lt_u32_e64 s[52:53], 9, v71
	v_addc_co_u32_e64 v34, s[44:45], 0, v34, s[44:45]
	v_cmp_ge_f32_e64 s[44:45], v59, v70
	s_or_b64 s[42:43], s[42:43], s[54:55]
	v_cmp_lt_u32_e64 s[54:55], 11, v71
	v_cndmask_b32_e64 v35, 0, 1, s[44:45]
	v_cmp_ge_f32_e64 s[44:45], v61, v70
	v_cmp_lt_u32_e64 s[56:57], 13, v71
	v_cmp_lt_u32_e64 s[58:59], 17, v71
	v_addc_co_u32_e64 v34, s[44:45], v34, v35, s[44:45]
	v_cmp_ge_f32_e64 s[44:45], v60, v70
	v_add_u32_e32 v1, 0xb000, v0
	v_add_u32_e32 v2, 0xf1fc, v0
	v_cndmask_b32_e64 v72, 0, 1, s[44:45]
	v_cmp_gt_f32_e64 s[44:45], v56, v70
	s_or_b64 s[44:45], s[44:45], s[46:47]
	v_cmp_eq_f32_e64 s[46:47], v54, v70
	s_and_b64 s[60:61], s[46:47], s[48:49]
	v_cmp_eq_f32_e64 s[48:49], v16, v70
	v_cmp_gt_f32_e64 s[46:47], v16, v70
	s_and_b64 s[48:49], s[6:7], s[48:49]
	s_or_b64 s[46:47], s[46:47], s[48:49]
	v_cmp_eq_f32_e64 s[48:49], v55, v70
	s_and_b64 s[62:63], s[48:49], s[50:51]
	v_cmp_eq_f32_e64 s[50:51], v50, v70
	v_cmp_gt_f32_e64 s[48:49], v50, v70
	s_and_b64 s[50:51], s[50:51], s[52:53]
	s_or_b64 s[48:49], s[48:49], s[50:51]
	v_cmp_eq_f32_e64 s[50:51], v51, v70
	v_cmp_lt_u32_e64 s[52:53], 10, v71
	s_and_b64 s[64:65], s[50:51], s[52:53]
	v_cmp_eq_f32_e64 s[52:53], v44, v70
	v_cmp_gt_f32_e64 s[50:51], v44, v70
	s_and_b64 s[52:53], s[52:53], s[54:55]
	s_or_b64 s[50:51], s[50:51], s[52:53]
	v_cmp_eq_f32_e64 s[52:53], v42, v70
	v_cmp_lt_u32_e64 s[54:55], 12, v71
	s_and_b64 s[66:67], s[52:53], s[54:55]
	v_cmp_eq_f32_e64 s[54:55], v45, v70
	v_cmp_gt_f32_e64 s[52:53], v45, v70
; DEVI void nsa_item(const Ctx& cx, const unsigned* cflag, int b, int g, int qt, unsigned char* lds, int wv) {
;     ...
;       float raw = impA[tl2 * 33 + j] + (j > 0 ? impB[tl2 * 33 + j - 1] : 0.f);
;       bool valid = j <= cur, forced = (j == 0) | (j == cur) | (j == cur - 1);
;       a[j] = valid ? (forced ? 1e9f : raw) : -1e30f;
;     }
;     unsigned bits = 0u;
; #pragma unroll
;     for (int e = 0; e < 8; ++e) {
;       const int m = sub * 8 + e;
;       float raw = impA[tl2 * 33 + m] + (m > 0 ? impB[tl2 * 33 + m - 1] : 0.f);
;       bool valid = m <= cur, forced = (m == 0) | (m == cur) | (m == cur - 1);
;       const float am = valid ? (forced ? 1e9f : raw) : -1e30f;
;       int rank = 0;
; #pragma unroll
;       for (int j = 0; j < 32; ++j) rank += (a[j] > am || (a[j] == am && j < m)) ? 1 : 0;
;       if (rank < 16 && valid) bits |= 1u << m;
	s_and_b64 s[54:55], s[54:55], s[56:57]
	s_or_b64 s[52:53], s[52:53], s[54:55]
	v_cmp_eq_f32_e64 s[54:55], v43, v70
	v_cmp_lt_u32_e64 s[56:57], 14, v71
	s_and_b64 s[82:83], s[54:55], s[56:57]
	v_cmp_eq_f32_e64 s[54:55], v27, v70
	v_cmp_lt_u32_e64 s[56:57], 16, v71
	s_and_b64 s[68:69], s[54:55], s[56:57]
	v_cmp_eq_f32_e64 s[56:57], v25, v70
	v_cmp_gt_f32_e64 s[54:55], v25, v70
	s_and_b64 s[56:57], s[56:57], s[58:59]
	s_or_b64 s[54:55], s[54:55], s[56:57]
	v_cndmask_b32_e64 v35, 0, 1, s[54:55]
	v_cmp_eq_f32_e64 s[54:55], v17, v70
	v_cmp_lt_u32_e64 s[56:57], 18, v71
	s_and_b64 s[72:73], s[54:55], s[56:57]
	v_cmp_eq_f32_e64 s[56:57], v28, v70
	v_cmp_lt_u32_e64 s[58:59], 19, v71
	v_cmp_gt_f32_e64 s[54:55], v28, v70
	s_and_b64 s[56:57], s[56:57], s[58:59]
	s_or_b64 s[54:55], s[54:55], s[56:57]
	v_cndmask_b32_e64 v62, 0, 1, s[54:55]
	v_cmp_eq_f32_e64 s[54:55], v26, v70
	v_cmp_lt_u32_e64 s[56:57], 20, v71
	s_and_b64 s[70:71], s[54:55], s[56:57]
	v_cmp_eq_f32_e64 s[56:57], v24, v70
	v_cmp_lt_u32_e64 s[58:59], 21, v71
	v_cmp_gt_f32_e64 s[54:55], v24, v70
	s_and_b64 s[56:57], s[56:57], s[58:59]
	s_or_b64 s[54:55], s[54:55], s[56:57]
	v_cndmask_b32_e64 v63, 0, 1, s[54:55]
	v_cmp_eq_f32_e64 s[54:55], v13, v70
	v_cmp_lt_u32_e64 s[56:57], 22, v71
	s_and_b64 s[74:75], s[54:55], s[56:57]
	v_cmp_eq_f32_e64 s[56:57], v12, v70
	v_cmp_gt_f32_e64 s[54:55], v12, v70
	s_and_b64 s[56:57], s[4:5], s[56:57]
	s_or_b64 s[54:55], s[54:55], s[56:57]
	v_cndmask_b32_e64 v64, 0, 1, s[54:55]
	v_cmp_eq_f32_e64 s[54:55], v11, v70
	v_cmp_lt_u32_e64 s[56:57], 24, v71
	s_and_b64 s[76:77], s[54:55], s[56:57]
	v_cmp_eq_f32_e64 s[56:57], v9, v70
	v_cmp_lt_u32_e64 s[58:59], 25, v71
	v_cmp_gt_f32_e64 s[54:55], v9, v70
	s_and_b64 s[56:57], s[56:57], s[58:59]
	s_or_b64 s[54:55], s[54:55], s[56:57]
	v_cndmask_b32_e64 v65, 0, 1, s[54:55]
	v_cmp_eq_f32_e64 s[54:55], v10, v70
	v_cmp_lt_u32_e64 s[56:57], 26, v71
	s_and_b64 s[78:79], s[54:55], s[56:57]
	v_cmp_eq_f32_e64 s[56:57], v8, v70
	v_cmp_lt_u32_e64 s[58:59], 27, v71
	v_cmp_gt_f32_e64 s[54:55], v8, v70
	s_and_b64 s[56:57], s[56:57], s[58:59]
	s_or_b64 s[54:55], s[54:55], s[56:57]
	v_cndmask_b32_e64 v71, 0, 1, s[54:55]
	v_cmp_eq_f32_e64 s[54:55], v5, v70
	s_and_b64 s[80:81], s[4:5], s[54:55]
	v_cmp_gt_f32_e64 s[54:55], v4, v70
	v_cndmask_b32_e64 v73, 0, 1, s[44:45]
	v_cmp_gt_f32_e64 s[44:45], v54, v70
	v_cndmask_b32_e64 v78, 0, 1, s[54:55]
	v_cmp_gt_f32_e64 s[54:55], v6, v70
	s_or_b64 s[44:45], s[44:45], s[60:61]
	v_cndmask_b32_e64 v74, 0, 1, s[46:47]
	v_addc_co_u32_e64 v34, s[54:55], v34, v72, s[54:55]
	v_cmp_gt_f32_e64 s[54:55], v7, v70
	v_cmp_gt_f32_e64 s[46:47], v55, v70
	v_cndmask_b32_e64 v75, 0, 1, s[48:49]
	v_addc_co_u32_e64 v34, s[54:55], v34, v78, s[54:55]
	v_addc_co_u32_e64 v34, s[44:45], v34, v73, s[44:45]
	s_or_b64 s[44:45], s[46:47], s[62:63]
	v_cmp_gt_f32_e64 s[48:49], v51, v70
	v_addc_co_u32_e64 v34, s[44:45], v34, v74, s[44:45]
	s_or_b64 s[44:45], s[48:49], s[64:65]
	v_cndmask_b32_e64 v76, 0, 1, s[50:51]
	v_cmp_gt_f32_e64 s[50:51], v42, v70
	v_addc_co_u32_e64 v34, s[44:45], v34, v75, s[44:45]
	ds_read2_b32 v[0:1], v1 offset1:1
	ds_read2_b32 v[2:3], v2 offset1:1
	s_or_b64 s[44:45], s[50:51], s[66:67]
	v_cndmask_b32_e64 v77, 0, 1, s[52:53]
	v_cmp_gt_f32_e64 s[52:53], v43, v70
	v_addc_co_u32_e64 v34, s[44:45], v34, v76, s[44:45]
	s_or_b64 s[44:45], s[52:53], s[82:83]
	s_nop 0
	v_addc_co_u32_e64 v72, s[44:45], v34, v77, s[44:45]
	v_or_b32_e32 v34, 7, v66
	v_cmp_eq_u32_e64 s[44:45], v38, v68
	v_cmp_eq_u32_e64 s[66:67], v38, v69
	s_waitcnt lgkmcnt(0)
	v_pk_add_f32 v[0:1], v[0:1], v[2:3]
	v_cmp_eq_u32_e64 s[64:65], v34, v68
	s_or_b64 s[44:45], s[44:45], s[66:67]
	v_cmp_eq_u32_e64 s[66:67], v34, v69
	v_cndmask_b32_e64 v0, v0, v239, s[44:45]
	s_or_b64 s[44:45], s[64:65], s[66:67]
	v_cndmask_b32_e64 v1, v1, v239, s[44:45]
	v_cmp_le_i32_e64 s[44:45], v38, v68
	v_cmp_lt_u32_e64 s[48:49], 8, v38
	v_cmp_lt_u32_e64 s[52:53], 9, v38
	v_cndmask_b32_e64 v0, v238, v0, s[44:45]
	v_cmp_ge_f32_e64 s[64:65], v58, v0
	v_cmp_eq_f32_e64 s[66:67], v54, v0
	s_and_b64 s[66:67], s[6:7], s[66:67]
	v_cndmask_b32_e64 v2, 0, 1, s[64:65]
	v_cmp_ge_f32_e64 s[64:65], v67, v0
	v_cmp_lt_u32_e64 s[54:55], 10, v38
	v_cmp_lt_u32_e64 s[56:57], 11, v38
	v_addc_co_u32_e64 v2, s[64:65], 0, v2, s[64:65]
	v_cmp_ge_f32_e64 s[64:65], v59, v0
	v_cmp_lt_u32_e64 s[58:59], 12, v38
	v_cmp_lt_u32_e64 s[60:61], 13, v38
	v_cndmask_b32_e64 v3, 0, 1, s[64:65]
	v_cmp_ge_f32_e64 s[64:65], v61, v0
	v_cmp_lt_u32_e64 s[62:63], 14, v38
	v_cmp_lt_u32_e64 s[50:51], 16, v38
	v_addc_co_u32_e64 v2, s[64:65], v2, v3, s[64:65]
	v_cmp_ge_f32_e64 s[64:65], v60, v0
	v_cmp_lt_u32_e64 s[46:47], 17, v38
	v_addc_co_u32_e64 v14, s[12:13], v15, v14, s[12:13]
	v_cndmask_b32_e64 v3, 0, 1, s[64:65]
	v_cmp_ge_f32_e64 s[64:65], v56, v0
	v_cmp_gt_u32_e64 s[12:13], 16, v14
	s_and_b64 s[0:1], s[12:13], s[0:1]
	v_addc_co_u32_e64 v2, s[64:65], v2, v3, s[64:65]
	v_cmp_gt_f32_e64 s[64:65], v54, v0
	s_or_b64 s[64:65], s[64:65], s[66:67]
	v_cmp_gt_f32_e64 s[66:67], v4, v0
	v_cndmask_b32_e64 v3, 0, 1, s[64:65]
	v_cmp_gt_f32_e64 s[64:65], v16, v0
	v_cndmask_b32_e64 v69, 0, 1, s[66:67]
	v_cmp_gt_f32_e64 s[66:67], v7, v0
	v_and_b32_e32 v36, 15, v36
	v_bcnt_u32_b32 v36, v36, 0
	v_addc_co_u32_e64 v2, s[66:67], v2, v69, s[66:67]
	v_cmp_eq_f32_e64 s[66:67], v16, v0
	s_and_b64 s[66:67], s[6:7], s[66:67]
	s_or_b64 s[64:65], s[64:65], s[66:67]
	v_cmp_eq_f32_e64 s[66:67], v55, v0
	s_and_b64 s[66:67], s[66:67], s[48:49]
	v_cmp_gt_f32_e64 s[48:49], v55, v0
	s_or_b64 s[48:49], s[48:49], s[66:67]
	v_cmp_lt_u32_e64 s[66:67], 18, v38
	v_cndmask_b32_e64 v69, 0, 1, s[48:49]
	v_cmp_eq_f32_e64 s[48:49], v50, v0
; DEVI void nsa_item(const Ctx& cx, const unsigned* cflag, int b, int g, int qt, unsigned char* lds, int wv) {
;     ...
;     for (int e = 0; e < 8; ++e) {
;       const int m = sub * 8 + e;
;       float raw = impA[tl2 * 33 + m] + (m > 0 ? impB[tl2 * 33 + m - 1] : 0.f);
;       bool valid = m <= cur, forced = (m == 0) | (m == cur) | (m == cur - 1);
;       const float am = valid ? (forced ? 1e9f : raw) : -1e30f;
;       int rank = 0;
; #pragma unroll
;       for (int j = 0; j < 32; ++j) rank += (a[j] > am || (a[j] == am && j < m)) ? 1 : 0;
;       if (rank < 16 && valid) bits |= 1u << m;
	s_and_b64 s[82:83], s[48:49], s[52:53]
	v_addc_co_u32_e64 v2, s[48:49], v2, v3, s[64:65]
	v_cmp_eq_f32_e64 s[64:65], v51, v0
	v_cmp_gt_f32_e64 s[48:49], v50, v0
	s_and_b64 s[64:65], s[64:65], s[54:55]
	v_cmp_gt_f32_e64 s[54:55], v51, v0
	s_or_b64 s[48:49], s[48:49], s[82:83]
	s_or_b64 s[64:65], s[54:55], s[64:65]
	v_cndmask_b32_e64 v3, 0, 1, s[64:65]
	v_cmp_eq_f32_e64 s[64:65], v44, v0
	v_addc_co_u32_e64 v2, s[48:49], v2, v69, s[48:49]
	s_and_b64 s[64:65], s[64:65], s[56:57]
	v_cmp_gt_f32_e64 s[48:49], v44, v0
	s_or_b64 s[48:49], s[48:49], s[64:65]
	v_cmp_eq_f32_e64 s[64:65], v42, v0
	s_and_b64 s[64:65], s[64:65], s[58:59]
	v_cmp_gt_f32_e64 s[58:59], v42, v0
	s_or_b64 s[64:65], s[58:59], s[64:65]
	v_cndmask_b32_e64 v69, 0, 1, s[64:65]
	v_cmp_eq_f32_e64 s[64:65], v45, v0
	s_and_b64 s[84:85], s[64:65], s[60:61]
	v_cmp_eq_f32_e64 s[60:61], v43, v0
	s_and_b64 s[62:63], s[60:61], s[62:63]
	v_cmp_gt_f32_e64 s[60:61], v43, v0
	s_or_b64 s[62:63], s[60:61], s[62:63]
	v_cndmask_b32_e64 v73, 0, 1, s[62:63]
	v_cmp_eq_f32_e64 s[62:63], v27, v0
	s_and_b64 s[62:63], s[62:63], s[50:51]
	v_cmp_gt_f32_e64 s[50:51], v27, v0
	s_or_b64 s[62:63], s[50:51], s[62:63]
	v_cndmask_b32_e64 v74, 0, 1, s[62:63]
	v_cmp_eq_f32_e64 s[62:63], v25, v0
	s_and_b64 s[64:65], s[62:63], s[46:47]
	v_cmp_eq_f32_e64 s[46:47], v17, v0
	s_and_b64 s[62:63], s[46:47], s[66:67]
	v_cmp_gt_f32_e64 s[46:47], v17, v0
	s_or_b64 s[46:47], s[46:47], s[62:63]
	v_cmp_lt_u32_e64 s[52:53], 19, v38
	v_cndmask_b32_e64 v75, 0, 1, s[46:47]
	v_cmp_eq_f32_e64 s[46:47], v28, v0
	v_cmp_lt_u32_e64 s[54:55], 20, v38
	s_and_b64 s[66:67], s[46:47], s[52:53]
	v_cmp_eq_f32_e64 s[46:47], v26, v0
	s_and_b64 s[52:53], s[46:47], s[54:55]
	v_cmp_gt_f32_e64 s[46:47], v26, v0
	s_or_b64 s[46:47], s[46:47], s[52:53]
	v_cmp_lt_u32_e64 s[56:57], 21, v38
	v_cndmask_b32_e64 v76, 0, 1, s[46:47]
	v_cmp_eq_f32_e64 s[46:47], v24, v0
	v_cmp_lt_u32_e64 s[58:59], 22, v38
	s_and_b64 s[82:83], s[46:47], s[56:57]
	v_cmp_eq_f32_e64 s[46:47], v13, v0
	s_and_b64 s[54:55], s[46:47], s[58:59]
	v_cmp_gt_f32_e64 s[46:47], v13, v0
	s_or_b64 s[46:47], s[46:47], s[54:55]
	v_cmp_lt_u32_e64 s[60:61], 24, v38
	v_cmp_lt_u32_e64 s[50:51], 25, v38
	v_cmp_lt_u32_e64 s[62:63], 26, v38
	v_cmp_lt_u32_e64 s[52:53], 27, v38
	v_cmp_lt_u32_e64 s[54:55], 28, v38
	v_cndmask_b32_e64 v38, 0, 1, s[46:47]
	v_cmp_eq_f32_e64 s[46:47], v11, v0
	s_and_b64 s[56:57], s[46:47], s[60:61]
	v_cmp_gt_f32_e64 s[46:47], v11, v0
	s_or_b64 s[56:57], s[46:47], s[56:57]
	v_cmp_le_i32_e64 s[46:47], v34, v68
	v_cndmask_b32_e64 v68, 0, 1, s[56:57]
	v_cmp_eq_f32_e64 s[56:57], v9, v0
	s_and_b64 s[58:59], s[56:57], s[50:51]
	v_cmp_eq_f32_e64 s[50:51], v10, v0
	s_and_b64 s[56:57], s[50:51], s[62:63]
	v_cmp_gt_f32_e64 s[50:51], v10, v0
	s_or_b64 s[56:57], s[50:51], s[56:57]
	v_cmp_gt_f32_e64 s[50:51], v45, v0
	v_addc_co_u32_e64 v2, s[48:49], v2, v3, s[48:49]
	s_or_b64 s[48:49], s[50:51], s[84:85]
	v_cndmask_b32_e64 v1, v238, v1, s[46:47]
	v_addc_co_u32_e64 v2, s[48:49], v2, v69, s[48:49]
	v_cndmask_b32_e64 v77, 0, 1, s[56:57]
	v_cmp_eq_f32_e64 s[56:57], v8, v0
	v_cmp_ge_f32_e64 s[48:49], v61, v1
	s_and_b64 s[56:57], s[56:57], s[52:53]
	v_cmp_eq_f32_e64 s[52:53], v5, v0
	v_cndmask_b32_e64 v3, 0, 1, s[48:49]
	v_cmp_ge_f32_e64 s[48:49], v60, v1
	s_and_b64 s[54:55], s[52:53], s[54:55]
	v_cmp_gt_f32_e64 s[52:53], v5, v0
	v_cndmask_b32_e64 v60, 0, 1, s[48:49]
	v_cmp_ge_f32_e64 s[48:49], v59, v1
	s_or_b64 s[54:55], s[52:53], s[54:55]
	v_cmp_eq_f32_e64 s[52:53], v16, v1
	v_cndmask_b32_e64 v59, 0, 1, s[48:49]
	v_cmp_ge_f32_e64 s[48:49], v58, v1
	v_cmp_eq_f32_e64 s[50:51], v12, v1
	s_and_b64 s[52:53], s[6:7], s[52:53]
	v_cndmask_b32_e64 v58, 0, 1, s[48:49]
	v_cmp_ge_f32_e64 s[48:49], v56, v1
	v_cmp_gt_f32_e64 s[6:7], v12, v1
	s_and_b64 s[50:51], s[4:5], s[50:51]
	v_cndmask_b32_e64 v56, 0, 1, s[48:49]
	v_cmp_gt_f32_e64 s[48:49], v16, v1
	s_or_b64 s[6:7], s[6:7], s[50:51]
	v_cndmask_b32_e64 v16, 0, 1, s[6:7]
	s_or_b64 s[6:7], s[48:49], s[52:53]
	v_cmp_eq_f32_e64 s[48:49], v55, v1
	v_cmp_lt_u32_e64 s[50:51], 8, v34
	s_and_b64 s[52:53], s[48:49], s[50:51]
	v_cmp_eq_f32_e64 s[48:49], v50, v1
	v_cmp_lt_u32_e64 s[50:51], 9, v34
	s_and_b64 s[60:61], s[48:49], s[50:51]
	v_cmp_eq_f32_e64 s[48:49], v51, v1
	v_cmp_lt_u32_e64 s[50:51], 10, v34
	s_and_b64 s[50:51], s[48:49], s[50:51]
	v_cmp_gt_f32_e64 s[48:49], v51, v1
	s_or_b64 s[50:51], s[48:49], s[50:51]
	v_cndmask_b32_e64 v51, 0, 1, s[50:51]
	v_cmp_gt_f32_e64 s[50:51], v50, v1
	s_or_b64 s[50:51], s[50:51], s[60:61]
	v_cmp_gt_f32_e64 s[48:49], v55, v1
	v_addc_co_u32_e64 v50, s[50:51], 0, v51, s[50:51]
	s_or_b64 s[48:49], s[48:49], s[52:53]
	v_cmp_eq_f32_e64 s[50:51], v5, v1
	v_cmp_lt_u32_e64 s[52:53], 28, v34
	s_and_b64 s[60:61], s[50:51], s[52:53]
	v_cmp_eq_f32_e64 s[50:51], v6, v1
	v_cmp_lt_u32_e64 s[52:53], 29, v34
	s_and_b64 s[52:53], s[50:51], s[52:53]
	v_cmp_gt_f32_e64 s[50:51], v6, v1
	s_or_b64 s[52:53], s[50:51], s[52:53]
	v_cmp_eq_f32_e64 s[50:51], v6, v0
	v_cndmask_b32_e64 v78, 0, 1, s[54:55]
	v_cmp_eq_f32_e64 s[54:55], v12, v0
	s_and_b64 s[62:63], s[4:5], s[50:51]
	v_cmp_eq_f32_e64 s[50:51], v4, v1
	s_and_b64 s[54:55], s[4:5], s[54:55]
	v_cndmask_b32_e64 v51, 0, 1, s[52:53]
	s_and_b64 s[52:53], s[4:5], s[50:51]
	v_cmp_gt_f32_e64 s[4:5], v7, v1
	v_cmp_lt_u32_e64 s[50:51], 13, v34
	v_lshlrev_b16_e32 v3, 2, v3
	v_cndmask_b32_e64 v7, 0, 1, s[4:5]
	v_cmp_eq_f32_e64 s[4:5], v45, v1
	s_and_b64 s[84:85], s[4:5], s[50:51]
	v_cmp_eq_f32_e64 s[4:5], v44, v1
	v_cmp_lt_u32_e64 s[50:51], 11, v34
	s_and_b64 s[50:51], s[4:5], s[50:51]
	v_cmp_gt_f32_e64 s[4:5], v45, v1
	s_or_b64 s[4:5], s[4:5], s[84:85]
	v_lshlrev_b16_e32 v60, 3, v60
	v_cndmask_b32_e64 v45, 0, 1, s[4:5]
; DEVI void nsa_item(const Ctx& cx, const unsigned* cflag, int b, int g, int qt, unsigned char* lds, int wv) {
;     ...
;     for (int e = 0; e < 8; ++e) {
;       const int m = sub * 8 + e;
;       float raw = impA[tl2 * 33 + m] + (m > 0 ? impB[tl2 * 33 + m - 1] : 0.f);
;       bool valid = m <= cur, forced = (m == 0) | (m == cur) | (m == cur - 1);
;       const float am = valid ? (forced ? 1e9f : raw) : -1e30f;
;       int rank = 0;
; #pragma unroll
;       for (int j = 0; j < 32; ++j) rank += (a[j] > am || (a[j] == am && j < m)) ? 1 : 0;
;       if (rank < 16 && valid) bits |= 1u << m;
	v_cmp_gt_f32_e64 s[4:5], v44, v1
	s_or_b64 s[4:5], s[4:5], s[50:51]
	v_cmp_lt_u32_e64 s[50:51], 14, v34
	v_cndmask_b32_e64 v44, 0, 1, s[4:5]
	v_cmp_eq_f32_e64 s[4:5], v43, v1
	s_and_b64 s[84:85], s[4:5], s[50:51]
	v_cmp_eq_f32_e64 s[4:5], v42, v1
	v_cmp_lt_u32_e64 s[50:51], 12, v34
	s_and_b64 s[50:51], s[4:5], s[50:51]
	v_cmp_gt_f32_e64 s[4:5], v43, v1
	s_or_b64 s[4:5], s[4:5], s[84:85]
	v_or_b32_e32 v3, v60, v3
	v_cndmask_b32_e64 v43, 0, 1, s[4:5]
	v_cmp_gt_f32_e64 s[4:5], v42, v1
	s_or_b64 s[4:5], s[4:5], s[50:51]
	v_cmp_lt_u32_e64 s[50:51], 26, v34
	v_cndmask_b32_e64 v42, 0, 1, s[4:5]
	v_cmp_eq_f32_e64 s[4:5], v10, v1
	v_lshlrev_b32_e64 v60, v66, 1
	s_and_b64 s[84:85], s[4:5], s[50:51]
	v_cmp_eq_f32_e64 s[4:5], v11, v1
	v_cmp_lt_u32_e64 s[50:51], 24, v34
	v_cndmask_b32_e64 v14, 0, v60, s[0:1]
	v_addc_co_u32_e64 v15, s[0:1], v19, v18, s[16:17]
	s_and_b64 s[50:51], s[4:5], s[50:51]
	v_cmp_gt_f32_e64 s[4:5], v10, v1
	v_cmp_gt_u32_e64 s[0:1], 16, v15
	s_or_b64 s[4:5], s[4:5], s[84:85]
	v_lshlrev_b32_e64 v61, v66, 2
	s_and_b64 s[0:1], s[0:1], s[10:11]
	v_lshlrev_b16_e32 v59, 1, v59
	v_cndmask_b32_e64 v55, 0, 1, s[4:5]
	v_cmp_gt_f32_e64 s[4:5], v11, v1
	v_cndmask_b32_e64 v15, 0, v61, s[0:1]
	v_cmp_gt_f32_e64 s[16:17], v11, v70
	v_addc_co_u32_e64 v11, s[0:1], v21, v20, s[18:19]
	v_or_b32_e32 v58, v58, v59
	s_or_b64 s[4:5], s[4:5], s[50:51]
	v_cmp_gt_u32_e64 s[0:1], 16, v11
	v_bitop3_b16 v3, v58, v3, 3 bitop3:0xec
	v_cndmask_b32_e64 v58, 0, 1, s[4:5]
	v_cmp_eq_f32_e64 s[4:5], v8, v1
	v_cmp_lt_u32_e64 s[50:51], 27, v34
	v_lshlrev_b32_e64 v69, v66, 4
	s_and_b64 s[0:1], s[0:1], s[14:15]
	s_and_b64 s[84:85], s[4:5], s[50:51]
	v_cmp_eq_f32_e64 s[4:5], v9, v1
	v_cmp_lt_u32_e64 s[50:51], 25, v34
	v_cmp_gt_f32_e64 s[14:15], v10, v70
	v_cndmask_b32_e64 v10, 0, v69, s[0:1]
	v_addc_co_u32_e64 v19, s[0:1], v30, v22, s[24:25]
	s_and_b64 s[50:51], s[4:5], s[50:51]
	v_cmp_gt_f32_e64 s[4:5], v9, v1
	v_cmp_gt_u32_e64 s[0:1], 16, v19
	s_or_b64 s[50:51], s[4:5], s[50:51]
	v_cmp_gt_f32_e64 s[4:5], v8, v1
	s_and_b64 s[0:1], s[0:1], s[20:21]
	s_or_b64 s[4:5], s[4:5], s[84:85]
	v_cndmask_b32_e64 v19, 0, v79, s[0:1]
	v_addc_co_u32_e64 v20, s[0:1], v37, v36, s[28:29]
	v_addc_co_u32_e64 v21, s[0:1], v40, v39, s[34:35]
	v_cndmask_b32_e64 v59, 0, 1, s[4:5]
	v_cmp_ge_f32_e64 s[4:5], v67, v1
	v_addc_co_u32_e64 v22, s[0:1], v46, v41, s[36:37]
	v_addc_co_u32_e64 v30, s[0:1], v48, v47, s[38:39]
	v_cmp_gt_f32_e64 s[38:39], v12, v0
	v_addc_co_u32_e64 v12, s[0:1], v57, v52, s[42:43]
	v_cmp_gt_f32_e64 s[42:43], v9, v0
	v_addc_co_u32_e64 v9, s[0:1], v31, v23, s[26:27]
	v_cmp_gt_f32_e64 s[26:27], v8, v0
	v_add_u32_e32 v8, v20, v21
	v_addc_co_u32_e64 v21, s[0:1], v49, v53, s[40:41]
	v_addc_co_u32_e64 v56, s[4:5], 0, v56, s[4:5]
	v_add_u32_e32 v20, v22, v30
	v_add3_u32 v9, v12, v9, v21
	v_and_b32_e32 v3, 15, v3
	v_cmp_ge_f32_e64 s[4:5], v54, v1
	v_add3_u32 v8, v8, v20, v9
	v_bcnt_u32_b32 v3, v3, 0
	v_cndmask_b32_e64 v81, 0, 1, s[50:51]
	v_addc_co_u32_e64 v7, s[4:5], 0, v7, s[4:5]
	v_cmp_eq_f32_e64 s[50:51], v29, v70
	v_cmp_gt_u32_e64 s[0:1], 16, v8
	v_cmp_gt_f32_e64 s[4:5], v29, v70
	v_addc_co_u32_e64 v16, s[6:7], 0, v16, s[6:7]
	v_addc_co_u32_e64 v3, s[6:7], v50, v3, s[48:49]
	s_and_b64 s[0:1], s[0:1], s[22:23]
	s_and_b64 s[40:41], s[50:51], s[8:9]
	v_cmp_gt_f32_e64 s[6:7], v27, v70
	v_cmp_gt_f32_e64 s[18:19], v5, v70
	v_cmp_gt_f32_e64 s[20:21], v29, v0
	v_cmp_eq_f32_e64 s[24:25], v29, v0
	v_cmp_gt_f32_e64 s[28:29], v25, v0
	v_cmp_gt_f32_e64 s[34:35], v28, v0
	v_cmp_gt_f32_e64 s[36:37], v24, v0
	v_cmp_gt_f32_e64 s[22:23], v6, v0
	v_cndmask_b32_e64 v0, 0, v80, s[0:1]
	v_cmp_gt_f32_e64 s[0:1], v5, v1
	s_or_b64 s[40:41], s[4:5], s[40:41]
	v_cmp_gt_f32_e64 s[4:5], v4, v1
	v_add_u16_e32 v4, v44, v42
	v_add_u16_e32 v5, v45, v43
	v_add_u16_e32 v4, v5, v4
	v_cndmask_b32_e64 v5, 0, 1, s[40:41]
	s_or_b64 s[6:7], s[6:7], s[68:69]
	v_cmp_gt_f32_e64 s[12:13], v17, v70
	v_addc_co_u32_e64 v5, s[6:7], v72, v5, s[6:7]
	s_or_b64 s[6:7], s[12:13], s[72:73]
	v_cmp_gt_f32_e64 s[48:49], v26, v70
	v_addc_co_u32_e64 v5, s[6:7], v5, v35, s[6:7]
	s_or_b64 s[6:7], s[48:49], s[70:71]
	v_cmp_gt_f32_e64 s[10:11], v13, v70
	v_addc_co_u32_e64 v5, s[6:7], v5, v62, s[6:7]
	s_or_b64 s[6:7], s[10:11], s[74:75]
	s_nop 0
; template <int M> DEVI unsigned shxu(unsigned v) { return (unsigned)__builtin_amdgcn_ds_swizzle((int)v, (M << 10) | 0x1f); }
; DEVI void nsa_item(const Ctx& cx, const unsigned* cflag, int b, int g, int qt, unsigned char* lds, int wv) {
;     ...
;     for (int e = 0; e < 8; ++e) {
;       const int m = sub * 8 + e;
;       float raw = impA[tl2 * 33 + m] + (m > 0 ? impB[tl2 * 33 + m - 1] : 0.f);
;       bool valid = m <= cur, forced = (m == 0) | (m == cur) | (m == cur - 1);
;       const float am = valid ? (forced ? 1e9f : raw) : -1e30f;
;       int rank = 0;
; #pragma unroll
;       for (int j = 0; j < 32; ++j) rank += (a[j] > am || (a[j] == am && j < m)) ? 1 : 0;
;       if (rank < 16 && valid) bits |= 1u << m;
;     }
;     bits |= shxu<1>(bits); bits |= shxu<2>(bits);
;     if (sub == 0) { selm[tl2] = bits; atomicOr(bmaskp, bits); }
	v_addc_co_u32_e64 v5, s[6:7], v5, v63, s[6:7]
	s_or_b64 s[6:7], s[16:17], s[76:77]
	s_nop 0
	v_addc_co_u32_e64 v5, s[6:7], v5, v64, s[6:7]
	s_or_b64 s[6:7], s[14:15], s[78:79]
	s_nop 0
	v_addc_co_u32_e64 v5, s[6:7], v5, v65, s[6:7]
	s_or_b64 s[6:7], s[18:19], s[80:81]
	s_nop 0
	v_addc_co_u32_e64 v5, s[6:7], v5, v71, s[6:7]
	v_cmp_gt_u32_e64 s[6:7], 16, v5
	v_lshlrev_b32_e64 v11, v66, 32
	s_and_b64 s[6:7], s[6:7], s[30:31]
	v_cndmask_b32_e64 v5, 0, v11, s[6:7]
	s_and_b64 s[6:7], s[24:25], s[8:9]
	s_or_b64 s[6:7], s[20:21], s[6:7]
	v_addc_co_u32_e64 v2, s[6:7], v2, v73, s[6:7]
	s_or_b64 s[6:7], s[28:29], s[64:65]
	s_nop 0
	v_addc_co_u32_e64 v2, s[6:7], v2, v74, s[6:7]
	s_or_b64 s[6:7], s[34:35], s[66:67]
	s_nop 0
	v_addc_co_u32_e64 v2, s[6:7], v2, v75, s[6:7]
	s_or_b64 s[6:7], s[36:37], s[82:83]
	s_nop 0
	v_addc_co_u32_e64 v2, s[6:7], v2, v76, s[6:7]
	s_or_b64 s[6:7], s[38:39], s[54:55]
	s_nop 0
	v_addc_co_u32_e64 v2, s[6:7], v2, v38, s[6:7]
	s_or_b64 s[6:7], s[42:43], s[58:59]
	s_nop 0
	v_addc_co_u32_e64 v2, s[6:7], v2, v68, s[6:7]
	s_or_b64 s[6:7], s[26:27], s[56:57]
	s_nop 0
	v_addc_co_u32_e64 v2, s[6:7], v2, v77, s[6:7]
	s_or_b64 s[6:7], s[22:23], s[62:63]
	s_nop 0
	v_addc_co_u32_e64 v2, s[6:7], v2, v78, s[6:7]
	v_cmp_gt_u32_e64 s[6:7], 16, v2
	v_lshlrev_b32_e64 v18, v66, 64
	s_and_b64 s[6:7], s[6:7], s[44:45]
	v_cmp_eq_f32_e64 s[14:15], v29, v1
	v_cmp_lt_u32_e64 s[40:41], 19, v34
	v_or_b32_e32 v9, v15, v14
	v_cndmask_b32_e64 v2, 0, v18, s[6:7]
	v_cmp_gt_f32_e64 s[6:7], v29, v1
	v_cmp_eq_f32_e64 s[12:13], v28, v1
	s_and_b64 s[8:9], s[14:15], s[8:9]
	v_or3_b32 v9, v9, v10, v19
	v_cmp_gt_f32_e64 s[10:11], v28, v1
	s_and_b64 s[12:13], s[12:13], s[40:41]
	s_or_b64 s[6:7], s[6:7], s[8:9]
	v_or3_b32 v0, v9, v0, v5
	v_cndmask_b32_e64 v5, 0, 1, s[6:7]
	s_or_b64 s[6:7], s[10:11], s[12:13]
	v_cmp_eq_f32_e64 s[12:13], v27, v1
	v_cmp_lt_u32_e64 s[16:17], 16, v34
	v_cndmask_b32_e64 v9, 0, 1, s[6:7]
	v_cmp_gt_f32_e64 s[6:7], v27, v1
	v_cmp_eq_f32_e64 s[10:11], v26, v1
	v_cmp_lt_u32_e64 s[14:15], 20, v34
	s_and_b64 s[12:13], s[12:13], s[16:17]
	v_cmp_gt_f32_e64 s[8:9], v26, v1
	s_and_b64 s[10:11], s[10:11], s[14:15]
	s_or_b64 s[6:7], s[6:7], s[12:13]
	v_cndmask_b32_e64 v10, 0, 1, s[6:7]
	s_or_b64 s[6:7], s[8:9], s[10:11]
	v_cmp_eq_f32_e64 s[12:13], v25, v1
	v_cmp_lt_u32_e64 s[16:17], 17, v34
	v_cndmask_b32_e64 v11, 0, 1, s[6:7]
	v_cmp_gt_f32_e64 s[6:7], v25, v1
	v_cmp_eq_f32_e64 s[10:11], v24, v1
	v_cmp_lt_u32_e64 s[14:15], 21, v34
	s_and_b64 s[12:13], s[12:13], s[16:17]
	v_cmp_gt_f32_e64 s[8:9], v24, v1
	s_and_b64 s[10:11], s[10:11], s[14:15]
	s_or_b64 s[6:7], s[6:7], s[12:13]
	v_cndmask_b32_e64 v12, 0, 1, s[6:7]
	s_or_b64 s[6:7], s[8:9], s[10:11]
	v_cmp_eq_f32_e64 s[12:13], v17, v1
	v_cmp_lt_u32_e64 s[16:17], 18, v34
	v_cndmask_b32_e64 v14, 0, 1, s[6:7]
	v_cmp_gt_f32_e64 s[6:7], v17, v1
	v_cmp_eq_f32_e64 s[10:11], v13, v1
	v_cmp_lt_u32_e64 s[14:15], 22, v34
	s_and_b64 s[12:13], s[12:13], s[16:17]
	v_cmp_gt_f32_e64 s[8:9], v13, v1
	s_and_b64 s[10:11], s[10:11], s[14:15]
	s_or_b64 s[6:7], s[6:7], s[12:13]
	v_add_u16_e32 v6, v58, v81
	v_add_u16_e32 v8, v55, v59
	v_cndmask_b32_e64 v1, 0, 1, s[6:7]
	s_or_b64 s[6:7], s[8:9], s[10:11]
	s_or_b64 s[0:1], s[0:1], s[60:61]
	v_cndmask_b32_e64 v13, 0, 1, s[6:7]
	v_add_u16_e32 v6, v8, v6
	v_addc_co_u32_e64 v8, s[0:1], v56, v51, s[0:1]
	v_add_u16_e32 v9, v9, v11
	v_add_u16_e32 v5, v5, v10
	v_add_u16_e32 v10, v14, v13
	v_add_u16_e32 v1, v12, v1
	s_or_b64 s[0:1], s[4:5], s[52:53]
	v_add_u16_e32 v1, v5, v1
	v_add_u16_e32 v5, v9, v10
	v_add_u32_e32 v3, v3, v4
	v_addc_co_u32_e64 v4, s[0:1], v7, v16, s[0:1]
	v_add_u16_e32 v1, v5, v1
	v_add3_u32 v4, v8, v6, v4
	v_add3_u32 v1, v3, v1, v4
	s_movk_i32 s58, 0x80
	v_cmp_gt_u32_e64 s[0:1], 16, v1
	v_lshlrev_b32_e64 v1, v66, s58
	s_and_b64 s[0:1], s[0:1], s[46:47]
	v_cndmask_b32_e64 v1, 0, v1, s[0:1]
	v_or3_b32 v0, v0, v2, v1
.Ltopk_join:
	ds_swizzle_b32 v1, v0 offset:swizzle(SWAP,1)
	s_waitcnt lgkmcnt(0)
	v_or_b32_e32 v0, v0, v1
	ds_swizzle_b32 v1, v0 offset:swizzle(SWAP,2)
	s_and_saveexec_b64 s[0:1], vcc
	s_cbranch_execz .LBB0_1420
	s_waitcnt lgkmcnt(0)
	v_or_b32_e32 v0, v0, v1
	v_lshl_add_u32 v1, v114, 2, 0
	s_mov_b64 s[4:5], exec
	v_add_u32_e32 v1, 0x13400, v1
	s_mov_b32 s6, 0
	ds_write_b32 v1, v0
